# prompt attention: partialSM VALU issued between the P.V MFMAs on the no-mask path (all six half-steps)
# speedup vs baseline: 1.0018x; 1.0018x over previous
.LBB0_1167:
	ds_read_b128 v[80:83], v189
	ds_read_b128 v[84:87], v189 offset:32
	ds_read_b128 v[64:67], v189 offset:128
	ds_read_b128 v[68:71], v189 offset:160
	ds_read_b128 v[88:91], v189 offset:64
	ds_read_b128 v[72:75], v189 offset:192
	ds_read_b128 v[92:95], v189 offset:96
	ds_read_b128 v[76:79], v189 offset:224
	ds_read_b128 v[206:209], v181 offset:49152
	ds_read_b128 v[210:213], v181 offset:57344
	v_add_f32_e32 v146, 0, v147
	v_add_f32_e32 v146, v148, v146
	v_add_f32_e32 v146, v149, v146
	s_waitcnt lgkmcnt(1)
	v_mfma_f32_32x32x16_bf16 v[80:95], v[206:209], v[126:129], v[80:95]
	v_add_f32_e32 v146, v202, v146
	v_add_f32_e32 v146, v203, v146
	v_add_f32_e32 v146, v205, v146
	v_add_f32_e32 v146, v201, v146
	v_add_f32_e32 v146, v204, v146
	v_add_f32_e32 v146, v193, v146
	v_add_f32_e32 v146, v195, v146
	s_waitcnt lgkmcnt(0)
	v_mfma_f32_32x32x16_bf16 v[64:79], v[210:213], v[126:129], v[64:79]
	ds_read_b128 v[206:209], v182 offset:49152
	ds_read_b128 v[210:213], v182 offset:57344
	v_add_f32_e32 v146, v196, v146
	v_add_f32_e32 v146, v199, v146
	v_exp_f32_e32 v142, v142
	v_add_f32_e32 v146, v194, v146
	v_exp_f32_e32 v143, v143
	v_add_f32_e32 v146, v197, v146
	s_waitcnt lgkmcnt(1)
	v_mfma_f32_32x32x16_bf16 v[80:95], v[206:209], v[122:125], v[80:95]
	v_exp_f32_e32 v140, v140
	v_add_f32_e32 v146, v198, v146
	v_exp_f32_e32 v141, v141
	v_add_f32_e32 v146, v200, v146
	v_exp_f32_e32 v136, v136
	v_add_f32_e32 v146, v142, v146
	v_exp_f32_e32 v137, v137
	s_waitcnt lgkmcnt(0)
	v_mfma_f32_32x32x16_bf16 v[64:79], v[210:213], v[122:125], v[64:79]
	ds_read_b128 v[206:209], v180 offset:49152
	ds_read_b128 v[210:213], v180 offset:57344
	v_add_f32_e32 v146, v143, v146
	v_exp_f32_e32 v134, v134
	v_add_f32_e32 v146, v140, v146
	v_exp_f32_e32 v135, v135
	v_add_f32_e32 v146, v141, v146
	v_exp_f32_e32 v130, v130
	s_waitcnt lgkmcnt(1)
	v_mfma_f32_32x32x16_bf16 v[80:95], v[206:209], v[118:121], v[80:95]
	v_add_f32_e32 v146, v136, v146
	v_exp_f32_e32 v131, v131
	v_add_f32_e32 v146, v137, v146
	v_exp_f32_e32 v144, v144
	v_add_f32_e32 v146, v134, v146
	v_exp_f32_e32 v145, v145
	v_add_f32_e32 v146, v135, v146
	s_waitcnt lgkmcnt(0)
	v_mfma_f32_32x32x16_bf16 v[64:79], v[210:213], v[118:121], v[64:79]
	ds_read_b128 v[206:209], v151 offset:49152
	ds_read_b128 v[210:213], v151 offset:57344
	v_exp_f32_e32 v138, v138
	v_add_f32_e32 v146, v130, v146
	v_exp_f32_e32 v139, v139
	v_add_f32_e32 v146, v131, v146
	v_exp_f32_e32 v132, v132
	v_add_f32_e32 v146, v144, v146
	s_waitcnt lgkmcnt(1)
	v_mfma_f32_32x32x16_bf16 v[80:95], v[206:209], v[114:117], v[80:95]
	v_exp_f32_e32 v133, v133
	v_add_f32_e32 v146, v145, v146
	v_add_f32_e32 v146, v138, v146
	v_add_f32_e32 v146, v139, v146
	v_add_f32_e32 v146, v132, v146
	v_add_f32_e32 v190, v133, v146
	v_mov_b32_e32 v191, v190
	s_waitcnt lgkmcnt(0)
	v_mfma_f32_32x32x16_bf16 v[64:79], v[210:213], v[114:117], v[64:79]
	ds_read_b128 v[206:209], v181 offset:49280
	ds_read_b128 v[210:213], v181 offset:57472
	v_permlane32_swap_b32_e32 v190, v191
	v_cvt_pk_bf16_f32 v146, v147, v148
	v_cvt_pk_bf16_f32 v147, v149, v202
	v_cvt_pk_bf16_f32 v148, v203, v205
	v_cvt_pk_bf16_f32 v149, v201, v204
	s_waitcnt lgkmcnt(1)
	v_mfma_f32_32x32x16_bf16 v[80:95], v[206:209], v[110:113], v[80:95]
	v_cvt_pk_bf16_f32 v192, v193, v195
	v_cvt_pk_bf16_f32 v193, v196, v199
	v_cvt_pk_bf16_f32 v194, v194, v197
	v_cvt_pk_bf16_f32 v195, v198, v200
	v_cvt_pk_bf16_f32 v196, v142, v143
	v_cvt_pk_bf16_f32 v197, v140, v141
	v_cvt_pk_bf16_f32 v198, v136, v137
	s_waitcnt lgkmcnt(0)
	v_mfma_f32_32x32x16_bf16 v[64:79], v[210:213], v[110:113], v[64:79]
	ds_read_b128 v[206:209], v182 offset:49280
	ds_read_b128 v[210:213], v182 offset:57472
	v_cvt_pk_bf16_f32 v199, v134, v135
	v_cvt_pk_bf16_f32 v200, v130, v131
	v_cvt_pk_bf16_f32 v201, v144, v145
	v_cvt_pk_bf16_f32 v202, v138, v139
	v_cvt_pk_bf16_f32 v203, v132, v133
	v_permlane32_swap_b32_e32 v146, v148
	s_waitcnt lgkmcnt(1)
	v_mfma_f32_32x32x16_bf16 v[80:95], v[206:209], v[106:109], v[80:95]
	v_permlane32_swap_b32_e32 v147, v149
	v_permlane32_swap_b32_e32 v192, v194
	v_permlane32_swap_b32_e32 v193, v195
	v_permlane32_swap_b32_e32 v196, v198
	s_waitcnt lgkmcnt(0)
	v_mfma_f32_32x32x16_bf16 v[64:79], v[210:213], v[106:109], v[64:79]
	ds_read_b128 v[206:209], v180 offset:49280
	ds_read_b128 v[210:213], v180 offset:57472
	v_permlane32_swap_b32_e32 v197, v199
	v_permlane32_swap_b32_e32 v200, v202
	v_permlane32_swap_b32_e32 v201, v203
	s_waitcnt lgkmcnt(1)
	v_mfma_f32_32x32x16_bf16 v[80:95], v[206:209], v[102:105], v[80:95]
	s_waitcnt lgkmcnt(0)
	v_mfma_f32_32x32x16_bf16 v[64:79], v[210:213], v[102:105], v[64:79]
	ds_read_b128 v[206:209], v151 offset:49280
	ds_read_b128 v[210:213], v151 offset:57472
	s_waitcnt lgkmcnt(1)
	v_mfma_f32_32x32x16_bf16 v[80:95], v[206:209], v[98:101], v[80:95]
	s_waitcnt lgkmcnt(0)
	v_mfma_f32_32x32x16_bf16 v[64:79], v[210:213], v[98:101], v[64:79]
	v_lshl_add_u64 v[130:131], v[156:157], 0, v[96:97]
	v_lshl_add_u64 v[134:135], v[152:153], 0, v[96:97]
	v_lshl_add_u64 v[138:139], v[158:159], 0, v[96:97]
	v_lshl_add_u64 v[142:143], v[154:155], 0, v[96:97]
	global_load_dwordx4 v[130:133], v[130:131], off
	s_nop 0
	global_load_dwordx4 v[134:137], v[134:135], off
	s_nop 0
	global_load_dwordx4 v[138:141], v[138:139], off
	s_nop 0
	global_load_dwordx4 v[142:145], v[142:143], off
	s_sub_i32 s6, s92, 64
	s_cmp_le_i32 s6, s41
	s_cbranch_scc0 .Lpvm_1167a
	ds_read_b64_tr_b16 v[204:205], v174 offset:0
	ds_read_b64_tr_b16 v[206:207], v174 offset:0x800
	ds_read_b64_tr_b16 v[208:209], v174 offset:0x1000
	ds_read_b64_tr_b16 v[210:211], v174 offset:0x1800
	ds_read_b64_tr_b16 v[220:221], v174 offset:0x2000
	ds_read_b64_tr_b16 v[222:223], v174 offset:0x2800
	ds_read_b64_tr_b16 v[224:225], v174 offset:0x3000
	ds_read_b64_tr_b16 v[226:227], v174 offset:0x3800
	s_waitcnt lgkmcnt(0)
	s_nop 0
	v_mfma_f32_32x32x16_bf16 v[48:63], v[146:149], v[204:207], v[48:63]
	v_max_f32_e32 v230, v81, v81
	v_max_f32_e32 v231, v80, v80
	v_max_f32_e32 v230, v231, v230
	ds_read_b64_tr_b16 v[204:205], v174 offset:0x200
	ds_read_b64_tr_b16 v[206:207], v174 offset:0xa00
	v_mfma_f32_32x32x16_bf16 v[48:63], v[192:195], v[208:211], v[48:63]
	v_max3_f32 v230, v230, v82, v83
	v_max3_f32 v230, v230, v84, v85
	v_max3_f32 v230, v230, v86, v87
	ds_read_b64_tr_b16 v[208:209], v174 offset:0x1200
	ds_read_b64_tr_b16 v[210:211], v174 offset:0x1a00
	v_mfma_f32_32x32x16_bf16 v[48:63], v[196:199], v[220:223], v[48:63]
	v_max3_f32 v230, v230, v88, v89
	v_max3_f32 v230, v230, v90, v91
	v_max3_f32 v230, v230, v92, v93
	ds_read_b64_tr_b16 v[220:221], v174 offset:0x2200
	ds_read_b64_tr_b16 v[222:223], v174 offset:0x2a00
	v_mfma_f32_32x32x16_bf16 v[48:63], v[200:203], v[224:227], v[48:63]
	v_max3_f32 v230, v230, v94, v95
	v_max3_f32 v230, v230, v64, v65
	v_max3_f32 v230, v230, v66, v67
	ds_read_b64_tr_b16 v[224:225], v174 offset:0x3200
	ds_read_b64_tr_b16 v[226:227], v174 offset:0x3a00
	s_waitcnt lgkmcnt(0)
	v_mfma_f32_32x32x16_bf16 v[32:47], v[146:149], v[204:207], v[32:47]
	v_max3_f32 v230, v230, v68, v69
	v_max3_f32 v230, v230, v70, v71
	v_max3_f32 v230, v230, v72, v73
	ds_read_b64_tr_b16 v[204:205], v174 offset:0x400
	ds_read_b64_tr_b16 v[206:207], v174 offset:0xc00
	v_mfma_f32_32x32x16_bf16 v[32:47], v[192:195], v[208:211], v[32:47]
	v_max3_f32 v230, v230, v74, v75
	v_max3_f32 v230, v230, v76, v77
	v_max3_f32 v230, v230, v78, v79
	ds_read_b64_tr_b16 v[208:209], v174 offset:0x1400
	ds_read_b64_tr_b16 v[210:211], v174 offset:0x1c00
	v_mfma_f32_32x32x16_bf16 v[32:47], v[196:199], v[220:223], v[32:47]
	v_mov_b32_e32 v231, v230
	s_nop 1
	v_permlane32_swap_b32_e32 v230, v231
	ds_read_b64_tr_b16 v[220:221], v174 offset:0x2400
	ds_read_b64_tr_b16 v[222:223], v174 offset:0x2c00
	v_mfma_f32_32x32x16_bf16 v[32:47], v[200:203], v[224:227], v[32:47]
	v_max_f32_e32 v231, v231, v231
	v_max_f32_e32 v230, v230, v230
	v_max_f32_e32 v230, v230, v231
	ds_read_b64_tr_b16 v[224:225], v174 offset:0x3400
	ds_read_b64_tr_b16 v[226:227], v174 offset:0x3c00
	s_waitcnt lgkmcnt(0)
	v_mfma_f32_32x32x16_bf16 v[16:31], v[146:149], v[204:207], v[16:31]
	v_sub_f32_e32 v231, v230, v187
	v_mul_f32_e32 v231, 0x3db504f3, v231
	s_mov_b32 s6, 0x41000000
	ds_read_b64_tr_b16 v[204:205], v174 offset:0x600
	ds_read_b64_tr_b16 v[206:207], v174 offset:0xe00
	v_mfma_f32_32x32x16_bf16 v[16:31], v[192:195], v[208:211], v[16:31]
	v_cmp_ge_f32_e32 vcc, s6, v231
	v_max_f32_e32 v231, v187, v187
	v_max_f32_e32 v230, v231, v230
	ds_read_b64_tr_b16 v[208:209], v174 offset:0x1600
	ds_read_b64_tr_b16 v[210:211], v174 offset:0x1e00
	v_mfma_f32_32x32x16_bf16 v[16:31], v[196:199], v[220:223], v[16:31]
	v_sub_f32_e32 v231, v187, v230
	v_mul_f32_e32 v231, 0x3e0293ee, v231
	v_exp_f32_e32 v231, v231
	ds_read_b64_tr_b16 v[220:221], v174 offset:0x2600
	ds_read_b64_tr_b16 v[222:223], v174 offset:0x2e00
	v_mfma_f32_32x32x16_bf16 v[16:31], v[200:203], v[224:227], v[16:31]
	ds_read_b64_tr_b16 v[224:225], v174 offset:0x3600
	ds_read_b64_tr_b16 v[226:227], v174 offset:0x3e00
	s_waitcnt lgkmcnt(0)
	v_mfma_f32_32x32x16_bf16 v[0:15], v[146:149], v[204:207], v[0:15]
	v_mfma_f32_32x32x16_bf16 v[0:15], v[192:195], v[208:211], v[0:15]
	v_mfma_f32_32x32x16_bf16 v[0:15], v[196:199], v[220:223], v[0:15]
	v_mfma_f32_32x32x16_bf16 v[0:15], v[200:203], v[224:227], v[0:15]
	s_nop 0
	v_mov_b32_e32 v146, v230
	v_mov_b32_e32 v147, v231
	s_branch .Lpvj_1167a
.Lpvm_1167a:
	ds_read_b64_tr_b16 v[204:205], v174 offset:0
	ds_read_b64_tr_b16 v[206:207], v174 offset:0x800
	ds_read_b64_tr_b16 v[208:209], v174 offset:0x1000
	ds_read_b64_tr_b16 v[210:211], v174 offset:0x1800
	ds_read_b64_tr_b16 v[220:221], v174 offset:0x2000
	ds_read_b64_tr_b16 v[222:223], v174 offset:0x2800
	ds_read_b64_tr_b16 v[224:225], v174 offset:0x3000
	ds_read_b64_tr_b16 v[226:227], v174 offset:0x3800
	s_waitcnt lgkmcnt(0)
	s_nop 0
	v_mfma_f32_32x32x16_bf16 v[48:63], v[146:149], v[204:207], v[48:63]
	ds_read_b64_tr_b16 v[204:205], v174 offset:0x200
	ds_read_b64_tr_b16 v[206:207], v174 offset:0xa00
	v_mfma_f32_32x32x16_bf16 v[48:63], v[192:195], v[208:211], v[48:63]
	ds_read_b64_tr_b16 v[208:209], v174 offset:0x1200
	ds_read_b64_tr_b16 v[210:211], v174 offset:0x1a00
	v_mfma_f32_32x32x16_bf16 v[48:63], v[196:199], v[220:223], v[48:63]
	ds_read_b64_tr_b16 v[220:221], v174 offset:0x2200
	ds_read_b64_tr_b16 v[222:223], v174 offset:0x2a00
	v_mfma_f32_32x32x16_bf16 v[48:63], v[200:203], v[224:227], v[48:63]
	ds_read_b64_tr_b16 v[224:225], v174 offset:0x3200
	ds_read_b64_tr_b16 v[226:227], v174 offset:0x3a00
	s_waitcnt lgkmcnt(0)
	v_mfma_f32_32x32x16_bf16 v[32:47], v[146:149], v[204:207], v[32:47]
	ds_read_b64_tr_b16 v[204:205], v174 offset:0x400
	ds_read_b64_tr_b16 v[206:207], v174 offset:0xc00
	v_mfma_f32_32x32x16_bf16 v[32:47], v[192:195], v[208:211], v[32:47]
	ds_read_b64_tr_b16 v[208:209], v174 offset:0x1400
	ds_read_b64_tr_b16 v[210:211], v174 offset:0x1c00
	v_mfma_f32_32x32x16_bf16 v[32:47], v[196:199], v[220:223], v[32:47]
	ds_read_b64_tr_b16 v[220:221], v174 offset:0x2400
	ds_read_b64_tr_b16 v[222:223], v174 offset:0x2c00
	v_mfma_f32_32x32x16_bf16 v[32:47], v[200:203], v[224:227], v[32:47]
	ds_read_b64_tr_b16 v[224:225], v174 offset:0x3400
	ds_read_b64_tr_b16 v[226:227], v174 offset:0x3c00
	s_waitcnt lgkmcnt(0)
	v_mfma_f32_32x32x16_bf16 v[16:31], v[146:149], v[204:207], v[16:31]
	ds_read_b64_tr_b16 v[204:205], v174 offset:0x600
	ds_read_b64_tr_b16 v[206:207], v174 offset:0xe00
	v_mfma_f32_32x32x16_bf16 v[16:31], v[192:195], v[208:211], v[16:31]
	ds_read_b64_tr_b16 v[208:209], v174 offset:0x1600
	ds_read_b64_tr_b16 v[210:211], v174 offset:0x1e00
	v_mfma_f32_32x32x16_bf16 v[16:31], v[196:199], v[220:223], v[16:31]
	ds_read_b64_tr_b16 v[220:221], v174 offset:0x2600
	ds_read_b64_tr_b16 v[222:223], v174 offset:0x2e00
	v_mfma_f32_32x32x16_bf16 v[16:31], v[200:203], v[224:227], v[16:31]
	ds_read_b64_tr_b16 v[224:225], v174 offset:0x3600
	ds_read_b64_tr_b16 v[226:227], v174 offset:0x3e00
	s_waitcnt lgkmcnt(0)
	v_mfma_f32_32x32x16_bf16 v[0:15], v[146:149], v[204:207], v[0:15]
	s_sub_i32 s6, s92, 64
	s_cmp_le_i32 s6, s41
	v_mfma_f32_32x32x16_bf16 v[0:15], v[192:195], v[208:211], v[0:15]
	v_mfma_f32_32x32x16_bf16 v[0:15], v[196:199], v[220:223], v[0:15]
	v_mfma_f32_32x32x16_bf16 v[0:15], v[200:203], v[224:227], v[0:15]
	s_cbranch_scc1 .LBB0_1169
	v_add_u32_e32 v146, 64, v188
	v_cmp_gt_i32_e64 s[66:67], 26, v146
	v_cmp_gt_i32_e64 s[68:69], 27, v146
	v_cmp_gt_i32_e64 s[64:65], 25, v146
	s_and_b64 s[66:67], s[68:69], s[66:67]
	v_cmp_gt_i32_e64 s[62:63], 24, v146
	s_and_b64 s[64:65], s[66:67], s[64:65]
	v_cmp_gt_i32_e64 s[60:61], 19, v146
	s_and_b64 s[62:63], s[64:65], s[62:63]
	v_cmp_gt_i32_e64 s[58:59], 18, v146
	s_and_b64 s[60:61], s[62:63], s[60:61]
	v_cmp_gt_i32_e64 s[56:57], 17, v146
	s_and_b64 s[58:59], s[60:61], s[58:59]
	v_cmp_gt_i32_e64 s[54:55], 16, v146
	s_and_b64 s[56:57], s[58:59], s[56:57]
	v_cmp_gt_i32_e64 s[52:53], 11, v146
	s_and_b64 s[54:55], s[56:57], s[54:55]
	v_cmp_gt_i32_e64 s[50:51], 10, v146
	s_and_b64 s[52:53], s[54:55], s[52:53]
	v_cmp_gt_i32_e64 s[48:49], 9, v146
	s_and_b64 s[50:51], s[52:53], s[50:51]
	v_cmp_gt_i32_e64 s[46:47], 8, v146
	s_and_b64 s[48:49], s[50:51], s[48:49]
	v_cmp_gt_i32_e64 s[44:45], 3, v146
	s_and_b64 s[46:47], s[48:49], s[46:47]
	v_cmp_gt_i32_e64 s[42:43], 2, v146
	s_and_b64 s[44:45], s[46:47], s[44:45]
	v_cmp_gt_i32_e64 s[38:39], 1, v146
	s_and_b64 s[42:43], s[44:45], s[42:43]
	v_cmp_gt_i32_e64 s[36:37], 0, v146
	s_and_b64 s[38:39], s[42:43], s[38:39]
	s_and_b64 s[36:37], s[38:39], s[36:37]
	v_cmp_gt_i32_e64 s[34:35], 58, v146
	v_cndmask_b32_e64 v80, v80, v232, s[36:37]
	v_cmp_gt_i32_e64 s[36:37], 59, v146
	v_cmp_gt_i32_e64 s[30:31], 57, v146
	s_and_b64 s[34:35], s[36:37], s[34:35]
	v_cmp_gt_i32_e64 s[28:29], 56, v146
	s_and_b64 s[30:31], s[34:35], s[30:31]
	v_cmp_gt_i32_e64 s[26:27], 51, v146
	s_and_b64 s[28:29], s[30:31], s[28:29]
	v_cmp_gt_i32_e64 s[24:25], 50, v146
	s_and_b64 s[26:27], s[28:29], s[26:27]
	v_cmp_gt_i32_e64 s[22:23], 49, v146
	s_and_b64 s[24:25], s[26:27], s[24:25]
	v_cmp_gt_i32_e64 s[20:21], 48, v146
	s_and_b64 s[22:23], s[24:25], s[22:23]
	v_cmp_gt_i32_e64 s[18:19], 43, v146
	s_and_b64 s[20:21], s[22:23], s[20:21]
	v_cmp_gt_i32_e64 s[16:17], 42, v146
	s_and_b64 s[18:19], s[20:21], s[18:19]
	v_cmp_gt_i32_e64 s[14:15], 41, v146
	s_and_b64 s[16:17], s[18:19], s[16:17]
	v_cmp_gt_i32_e64 s[12:13], 40, v146
	s_and_b64 s[14:15], s[16:17], s[14:15]
	v_cmp_gt_i32_e64 s[10:11], 35, v146
	s_and_b64 s[12:13], s[14:15], s[12:13]
	v_cmp_gt_i32_e64 s[8:9], 34, v146
	s_and_b64 s[10:11], s[12:13], s[10:11]
	v_cmp_gt_i32_e64 s[6:7], 33, v146
	s_and_b64 s[8:9], s[10:11], s[8:9]
	v_cmp_gt_i32_e32 vcc, 32, v146
	s_and_b64 s[6:7], s[8:9], s[6:7]
	s_and_b64 vcc, s[6:7], vcc
	v_cndmask_b32_e64 v95, v95, v232, s[68:69]
	v_cndmask_b32_e64 v94, v94, v232, s[66:67]
	v_cndmask_b32_e64 v93, v93, v232, s[64:65]
	v_cndmask_b32_e64 v92, v92, v232, s[62:63]
	v_cndmask_b32_e64 v91, v91, v232, s[60:61]
	v_cndmask_b32_e64 v90, v90, v232, s[58:59]
	v_cndmask_b32_e64 v89, v89, v232, s[56:57]
	v_cndmask_b32_e64 v88, v88, v232, s[54:55]
	v_cndmask_b32_e64 v87, v87, v232, s[52:53]
	v_cndmask_b32_e64 v86, v86, v232, s[50:51]
	v_cndmask_b32_e64 v85, v85, v232, s[48:49]
	v_cndmask_b32_e64 v84, v84, v232, s[46:47]
	v_cndmask_b32_e64 v83, v83, v232, s[44:45]
	v_cndmask_b32_e64 v82, v82, v232, s[42:43]
	v_cndmask_b32_e64 v81, v81, v232, s[38:39]
	v_cndmask_b32_e64 v79, v79, v232, s[36:37]
	v_cndmask_b32_e64 v78, v78, v232, s[34:35]
	v_cndmask_b32_e64 v77, v77, v232, s[30:31]
	v_cndmask_b32_e64 v76, v76, v232, s[28:29]
	v_cndmask_b32_e64 v75, v75, v232, s[26:27]
	v_cndmask_b32_e64 v74, v74, v232, s[24:25]
	v_cndmask_b32_e64 v73, v73, v232, s[22:23]
	v_cndmask_b32_e64 v72, v72, v232, s[20:21]
	v_cndmask_b32_e64 v71, v71, v232, s[18:19]
	v_cndmask_b32_e64 v70, v70, v232, s[16:17]
	v_cndmask_b32_e64 v69, v69, v232, s[14:15]
	v_cndmask_b32_e64 v68, v68, v232, s[12:13]
	v_cndmask_b32_e64 v67, v67, v232, s[10:11]
	v_cndmask_b32_e64 v66, v66, v232, s[8:9]
	v_cndmask_b32_e64 v65, v65, v232, s[6:7]
	v_cndmask_b32_e32 v64, v64, v232, vcc

.Lpvj_1167a:
	s_cmp_eq_u64 vcc, exec
	s_cselect_b64 s[6:7], -1, 0
	s_barrier
	s_waitcnt vmcnt(0)
	v_cndmask_b32_e64 v192, v147, 1.0, s[6:7]
	v_cmp_gt_f32_e32 vcc, 1.0, v192
	s_waitcnt vmcnt(3)
	ds_write_b128 v184, v[130:133]
	s_waitcnt vmcnt(2)
	ds_write_b128 v185, v[134:137]
	s_waitcnt vmcnt(1)
	ds_write_b128 v176, v[138:141] offset:32768
	s_waitcnt vmcnt(0)
	ds_write_b128 v176, v[142:145] offset:40960
	s_cbranch_vccz .LBB0_1173
	s_and_saveexec_b64 s[8:9], s[4:5]
	ds_write_b32 v173, v192 offset:128
	s_or_b64 exec, exec, s[8:9]
	s_waitcnt lgkmcnt(0)
	ds_read_b128 v[130:133], v169 offset:224
	ds_read_b128 v[134:137], v169 offset:192
	ds_read_b128 v[138:141], v169 offset:160
	ds_read_b128 v[142:145], v169 offset:128
	s_waitcnt lgkmcnt(3)
	v_pk_mul_f32 v[62:63], v[62:63], v[132:133]
	s_waitcnt lgkmcnt(2)
	v_pk_mul_f32 v[58:59], v[58:59], v[136:137]
	s_waitcnt lgkmcnt(1)
	v_pk_mul_f32 v[54:55], v[54:55], v[140:141]
	s_waitcnt lgkmcnt(0)
	v_pk_mul_f32 v[50:51], v[50:51], v[144:145]
	v_pk_mul_f32 v[60:61], v[60:61], v[130:131]
	v_pk_mul_f32 v[56:57], v[56:57], v[134:135]
	v_pk_mul_f32 v[52:53], v[52:53], v[138:139]
	v_pk_mul_f32 v[48:49], v[48:49], v[142:143]
	v_pk_mul_f32 v[46:47], v[46:47], v[132:133]
	v_pk_mul_f32 v[42:43], v[42:43], v[136:137]
	v_pk_mul_f32 v[38:39], v[38:39], v[140:141]
	v_pk_mul_f32 v[34:35], v[34:35], v[144:145]
	v_pk_mul_f32 v[44:45], v[44:45], v[130:131]
	v_pk_mul_f32 v[40:41], v[40:41], v[134:135]
	v_pk_mul_f32 v[36:37], v[36:37], v[138:139]
	v_pk_mul_f32 v[32:33], v[32:33], v[142:143]
	v_pk_mul_f32 v[30:31], v[30:31], v[132:133]
	v_pk_mul_f32 v[26:27], v[26:27], v[136:137]
	v_pk_mul_f32 v[22:23], v[22:23], v[140:141]
	v_pk_mul_f32 v[18:19], v[18:19], v[144:145]
	v_pk_mul_f32 v[28:29], v[28:29], v[130:131]
	v_pk_mul_f32 v[24:25], v[24:25], v[134:135]
	v_pk_mul_f32 v[20:21], v[20:21], v[138:139]
	v_pk_mul_f32 v[16:17], v[16:17], v[142:143]
	v_pk_mul_f32 v[14:15], v[14:15], v[132:133]
	v_pk_mul_f32 v[10:11], v[10:11], v[136:137]
	v_pk_mul_f32 v[6:7], v[6:7], v[140:141]
	v_pk_mul_f32 v[2:3], v[2:3], v[144:145]
	v_pk_mul_f32 v[12:13], v[12:13], v[130:131]
	v_pk_mul_f32 v[8:9], v[8:9], v[134:135]
	v_pk_mul_f32 v[4:5], v[4:5], v[138:139]
	v_pk_mul_f32 v[0:1], v[0:1], v[142:143]
.LBB0_1173:
	v_cndmask_b32_e64 v187, v146, v187, s[6:7]
	v_mul_f32_e32 v146, 0xbe0293ee, v187
	v_fmamk_f32 v80, v80, 0x3e0293ee, v146
	v_fmamk_f32 v81, v81, 0x3e0293ee, v146
	v_fmamk_f32 v82, v82, 0x3e0293ee, v146
	v_fmamk_f32 v83, v83, 0x3e0293ee, v146
	v_fmamk_f32 v84, v84, 0x3e0293ee, v146
	v_fmamk_f32 v85, v85, 0x3e0293ee, v146
	v_fmamk_f32 v86, v86, 0x3e0293ee, v146
	v_fmamk_f32 v87, v87, 0x3e0293ee, v146
	v_fmamk_f32 v88, v88, 0x3e0293ee, v146
	v_fmamk_f32 v89, v89, 0x3e0293ee, v146
	v_fmamk_f32 v90, v90, 0x3e0293ee, v146
	v_fmamk_f32 v91, v91, 0x3e0293ee, v146
	v_fmamk_f32 v92, v92, 0x3e0293ee, v146
	v_fmamk_f32 v93, v93, 0x3e0293ee, v146
	v_fmamk_f32 v94, v94, 0x3e0293ee, v146
	v_fmamk_f32 v95, v95, 0x3e0293ee, v146
	v_exp_f32_e32 v139, v80
	v_exp_f32_e32 v141, v81
	v_exp_f32_e32 v142, v82
	v_exp_f32_e32 v143, v83
	v_exp_f32_e32 v144, v84
	v_exp_f32_e32 v145, v85
	v_exp_f32_e32 v138, v86
	v_exp_f32_e32 v140, v87
	v_exp_f32_e32 v133, v88
	v_exp_f32_e32 v135, v89
	v_exp_f32_e32 v136, v90
	v_exp_f32_e32 v137, v91
	v_exp_f32_e32 v130, v92
	v_exp_f32_e32 v131, v93
	v_exp_f32_e32 v132, v94
	v_exp_f32_e32 v134, v95
	v_fmamk_f32 v198, v64, 0x3e0293ee, v146
	v_fmamk_f32 v199, v65, 0x3e0293ee, v146
	v_fmamk_f32 v200, v66, 0x3e0293ee, v146
	v_fmamk_f32 v201, v67, 0x3e0293ee, v146
	v_fmamk_f32 v202, v68, 0x3e0293ee, v146
	v_fmamk_f32 v148, v69, 0x3e0293ee, v146
	v_fmamk_f32 v149, v70, 0x3e0293ee, v146
	v_fmamk_f32 v193, v71, 0x3e0293ee, v146
	v_fmamk_f32 v194, v72, 0x3e0293ee, v146
	v_fmamk_f32 v195, v73, 0x3e0293ee, v146
	v_fmamk_f32 v196, v74, 0x3e0293ee, v146
	v_fmamk_f32 v197, v75, 0x3e0293ee, v146
	v_fmamk_f32 v147, v76, 0x3e0293ee, v146
	v_fmamk_f32 v203, v77, 0x3e0293ee, v146
	v_fmamk_f32 v204, v78, 0x3e0293ee, v146
	v_fmac_f32_e32 v146, 0x3e0293ee, v79
	s_waitcnt lgkmcnt(0)
	s_barrier
	ds_read_b128 v[80:83], v189 offset:256
	ds_read_b128 v[84:87], v189 offset:288
	ds_read_b128 v[64:67], v189 offset:384
	ds_read_b128 v[68:71], v189 offset:416
	ds_read_b128 v[88:91], v189 offset:320
	ds_read_b128 v[72:75], v189 offset:448
	ds_read_b128 v[92:95], v189 offset:352
	ds_read_b128 v[76:79], v189 offset:480
	ds_read_b128 v[206:209], v181 offset:32768
	ds_read_b128 v[210:213], v181 offset:40960
	v_exp_f32_e32 v218, v146
	v_add_f32_e32 v146, 0, v139
	v_add_f32_e32 v146, v141, v146
	s_waitcnt lgkmcnt(1)
	v_mfma_f32_32x32x16_bf16 v[80:95], v[206:209], v[126:129], v[80:95]
	v_add_f32_e32 v146, v142, v146
	v_add_f32_e32 v146, v143, v146
	v_add_f32_e32 v146, v144, v146
	v_add_f32_e32 v146, v145, v146
	v_add_f32_e32 v146, v138, v146
	v_add_f32_e32 v146, v140, v146
	v_add_f32_e32 v146, v133, v146
	s_waitcnt lgkmcnt(0)
	v_mfma_f32_32x32x16_bf16 v[64:79], v[210:213], v[126:129], v[64:79]
	ds_read_b128 v[206:209], v182 offset:32768
	ds_read_b128 v[210:213], v182 offset:40960
	v_add_f32_e32 v146, v135, v146
	v_add_f32_e32 v146, v136, v146
	v_add_f32_e32 v146, v137, v146
	v_exp_f32_e32 v198, v198
	v_add_f32_e32 v146, v130, v146
	v_exp_f32_e32 v199, v199
	s_waitcnt lgkmcnt(1)
	v_mfma_f32_32x32x16_bf16 v[80:95], v[206:209], v[122:125], v[80:95]
	v_add_f32_e32 v146, v131, v146
	v_exp_f32_e32 v200, v200
	v_add_f32_e32 v146, v132, v146
	v_exp_f32_e32 v201, v201
	v_add_f32_e32 v146, v134, v146
	v_exp_f32_e32 v202, v202
	v_add_f32_e32 v146, v198, v146
	s_waitcnt lgkmcnt(0)
	v_mfma_f32_32x32x16_bf16 v[64:79], v[210:213], v[122:125], v[64:79]
	ds_read_b128 v[206:209], v180 offset:32768
	ds_read_b128 v[210:213], v180 offset:40960
	v_exp_f32_e32 v205, v148
	v_add_f32_e32 v146, v199, v146
	v_add_f32_e32 v146, v200, v146
	v_exp_f32_e32 v193, v193
	v_add_f32_e32 v146, v201, v146
	v_add_f32_e32 v146, v202, v146
	s_waitcnt lgkmcnt(1)
	v_mfma_f32_32x32x16_bf16 v[80:95], v[206:209], v[118:121], v[80:95]
	v_add_f32_e32 v146, v205, v146
	v_exp_f32_e32 v214, v203
	v_exp_f32_e32 v215, v204
	v_cvt_pk_bf16_f32 v148, v144, v145
	v_cvt_pk_bf16_f32 v198, v198, v199
	v_cvt_pk_bf16_f32 v199, v200, v201
	v_cvt_pk_bf16_f32 v200, v202, v205
	s_waitcnt lgkmcnt(0)
	v_mfma_f32_32x32x16_bf16 v[64:79], v[210:213], v[118:121], v[64:79]
	ds_read_b128 v[206:209], v151 offset:32768
	ds_read_b128 v[210:213], v151 offset:40960
	v_cvt_pk_bf16_f32 v205, v215, v218
	v_permlane32_swap_b32_e32 v198, v200
	s_waitcnt lgkmcnt(1)
	v_mfma_f32_32x32x16_bf16 v[80:95], v[206:209], v[114:117], v[80:95]
	s_waitcnt lgkmcnt(0)
	v_mfma_f32_32x32x16_bf16 v[64:79], v[210:213], v[114:117], v[64:79]
	ds_read_b128 v[206:209], v181 offset:32896
	ds_read_b128 v[210:213], v181 offset:41088
	s_waitcnt lgkmcnt(1)
	v_mfma_f32_32x32x16_bf16 v[80:95], v[206:209], v[110:113], v[80:95]
	s_waitcnt lgkmcnt(0)
	v_mfma_f32_32x32x16_bf16 v[64:79], v[210:213], v[110:113], v[64:79]
	ds_read_b128 v[206:209], v182 offset:32896
	ds_read_b128 v[210:213], v182 offset:41088
	s_waitcnt lgkmcnt(1)
	v_mfma_f32_32x32x16_bf16 v[80:95], v[206:209], v[106:109], v[80:95]
	s_waitcnt lgkmcnt(0)
	v_mfma_f32_32x32x16_bf16 v[64:79], v[210:213], v[106:109], v[64:79]
	ds_read_b128 v[206:209], v180 offset:32896
	ds_read_b128 v[210:213], v180 offset:41088
	s_waitcnt lgkmcnt(1)
	v_mfma_f32_32x32x16_bf16 v[80:95], v[206:209], v[102:105], v[80:95]
	s_waitcnt lgkmcnt(0)
	v_mfma_f32_32x32x16_bf16 v[64:79], v[210:213], v[102:105], v[64:79]
	ds_read_b128 v[206:209], v151 offset:32896
	ds_read_b128 v[210:213], v151 offset:41088
	s_waitcnt lgkmcnt(1)
	v_mfma_f32_32x32x16_bf16 v[80:95], v[206:209], v[98:101], v[80:95]
	v_exp_f32_e32 v208, v149
	v_exp_f32_e32 v209, v194
	v_cvt_pk_bf16_f32 v149, v138, v140
	v_cvt_pk_bf16_f32 v194, v133, v135
	v_add_f32_e32 v146, v208, v146
	v_add_f32_e32 v146, v193, v146
	v_add_f32_e32 v146, v209, v146
	s_waitcnt lgkmcnt(0)
	v_mfma_f32_32x32x16_bf16 v[64:79], v[210:213], v[98:101], v[64:79]
	v_exp_f32_e32 v210, v195
	v_exp_f32_e32 v211, v196
	v_exp_f32_e32 v212, v197
	v_exp_f32_e32 v213, v147
	v_add_f32_e32 v146, v210, v146
	v_add_f32_e32 v146, v211, v146
	v_add_f32_e32 v146, v212, v146
	v_add_f32_e32 v146, v213, v146
	v_add_f32_e32 v146, v214, v146
	v_add_f32_e32 v146, v215, v146
	v_add_f32_e32 v206, v218, v146
	v_mov_b32_e32 v207, v206
	s_nop 1
	v_permlane32_swap_b32_e32 v206, v207
	v_cvt_pk_bf16_f32 v146, v139, v141
	v_cvt_pk_bf16_f32 v147, v142, v143
	v_cvt_pk_bf16_f32 v195, v136, v137
	v_cvt_pk_bf16_f32 v196, v130, v131
	v_cvt_pk_bf16_f32 v197, v132, v134
	v_cvt_pk_bf16_f32 v201, v208, v193
	v_cvt_pk_bf16_f32 v202, v209, v210
	v_cvt_pk_bf16_f32 v203, v211, v212
	v_cvt_pk_bf16_f32 v204, v213, v214
	v_permlane32_swap_b32_e32 v146, v148
	v_permlane32_swap_b32_e32 v147, v149
	v_permlane32_swap_b32_e32 v194, v196
	v_permlane32_swap_b32_e32 v195, v197
	v_permlane32_swap_b32_e32 v199, v201
	v_permlane32_swap_b32_e32 v202, v204
	v_permlane32_swap_b32_e32 v203, v205
	v_lshl_add_u64 v[130:131], v[164:165], 0, v[96:97]
	v_lshl_add_u64 v[134:135], v[160:161], 0, v[96:97]
	v_lshl_add_u64 v[138:139], v[166:167], 0, v[96:97]
	v_lshl_add_u64 v[142:143], v[162:163], 0, v[96:97]
	global_load_dwordx4 v[130:133], v[130:131], off
	s_nop 0
	global_load_dwordx4 v[134:137], v[134:135], off
	s_nop 0
	global_load_dwordx4 v[138:141], v[138:139], off
	s_nop 0
	global_load_dwordx4 v[142:145], v[142:143], off
	s_cmp_le_i32 s92, s41
	s_cbranch_scc0 .Lpvm_1167b
	ds_read_b64_tr_b16 v[208:209], v174 offset:0x4000
	ds_read_b64_tr_b16 v[210:211], v174 offset:0x4800
	ds_read_b64_tr_b16 v[220:221], v174 offset:0x5000
	ds_read_b64_tr_b16 v[222:223], v174 offset:0x5800
	ds_read_b64_tr_b16 v[224:225], v174 offset:0x6000
	ds_read_b64_tr_b16 v[226:227], v174 offset:0x6800
	ds_read_b64_tr_b16 v[238:239], v174 offset:0x7000
	ds_read_b64_tr_b16 v[240:241], v174 offset:0x7800
	s_waitcnt lgkmcnt(0)
	s_nop 0
	v_mfma_f32_32x32x16_bf16 v[48:63], v[146:149], v[208:211], v[48:63]
	v_max_f32_e32 v230, v81, v81
	v_max_f32_e32 v231, v80, v80
	v_max_f32_e32 v230, v231, v230
	ds_read_b64_tr_b16 v[208:209], v174 offset:0x4200
	ds_read_b64_tr_b16 v[210:211], v174 offset:0x4a00
	v_mfma_f32_32x32x16_bf16 v[48:63], v[194:197], v[220:223], v[48:63]
	v_max3_f32 v230, v230, v82, v83
	v_max3_f32 v230, v230, v84, v85
	v_max3_f32 v230, v230, v86, v87
	ds_read_b64_tr_b16 v[220:221], v174 offset:0x5200
	ds_read_b64_tr_b16 v[222:223], v174 offset:0x5a00
	v_mfma_f32_32x32x16_bf16 v[48:63], v[198:201], v[224:227], v[48:63]
	v_max3_f32 v230, v230, v88, v89
	v_max3_f32 v230, v230, v90, v91
	v_max3_f32 v230, v230, v92, v93
	ds_read_b64_tr_b16 v[224:225], v174 offset:0x6200
	ds_read_b64_tr_b16 v[226:227], v174 offset:0x6a00
	v_mfma_f32_32x32x16_bf16 v[48:63], v[202:205], v[238:241], v[48:63]
	v_max3_f32 v230, v230, v94, v95
	v_max3_f32 v230, v230, v64, v65
	v_max3_f32 v230, v230, v66, v67
	ds_read_b64_tr_b16 v[238:239], v174 offset:0x7200
	ds_read_b64_tr_b16 v[240:241], v174 offset:0x7a00
	s_waitcnt lgkmcnt(0)
	v_mfma_f32_32x32x16_bf16 v[32:47], v[146:149], v[208:211], v[32:47]
	v_max3_f32 v230, v230, v68, v69
	v_max3_f32 v230, v230, v70, v71
	v_max3_f32 v230, v230, v72, v73
	ds_read_b64_tr_b16 v[208:209], v174 offset:0x4400
	ds_read_b64_tr_b16 v[210:211], v174 offset:0x4c00
	v_mfma_f32_32x32x16_bf16 v[32:47], v[194:197], v[220:223], v[32:47]
	v_max3_f32 v230, v230, v74, v75
	v_max3_f32 v230, v230, v76, v77
	v_max3_f32 v230, v230, v78, v79
	ds_read_b64_tr_b16 v[220:221], v174 offset:0x5400
	ds_read_b64_tr_b16 v[222:223], v174 offset:0x5c00
	v_mfma_f32_32x32x16_bf16 v[32:47], v[198:201], v[224:227], v[32:47]
	v_mov_b32_e32 v231, v230
	s_nop 1
	v_permlane32_swap_b32_e32 v230, v231
	ds_read_b64_tr_b16 v[224:225], v174 offset:0x6400
	ds_read_b64_tr_b16 v[226:227], v174 offset:0x6c00
	v_mfma_f32_32x32x16_bf16 v[32:47], v[202:205], v[238:241], v[32:47]
	v_max_f32_e32 v231, v231, v231
	v_max_f32_e32 v230, v230, v230
	v_max_f32_e32 v230, v230, v231
	ds_read_b64_tr_b16 v[238:239], v174 offset:0x7400
	ds_read_b64_tr_b16 v[240:241], v174 offset:0x7c00
	s_waitcnt lgkmcnt(0)
	v_mfma_f32_32x32x16_bf16 v[16:31], v[146:149], v[208:211], v[16:31]
	v_sub_f32_e32 v231, v230, v187
	v_mul_f32_e32 v231, 0x3db504f3, v231
	s_mov_b32 s6, 0x41000000
	ds_read_b64_tr_b16 v[208:209], v174 offset:0x4600
	ds_read_b64_tr_b16 v[210:211], v174 offset:0x4e00
	v_mfma_f32_32x32x16_bf16 v[16:31], v[194:197], v[220:223], v[16:31]
	v_cmp_ge_f32_e32 vcc, s6, v231
	v_max_f32_e32 v231, v187, v187
	v_max_f32_e32 v231, v231, v230
	ds_read_b64_tr_b16 v[220:221], v174 offset:0x5600
	ds_read_b64_tr_b16 v[222:223], v174 offset:0x5e00
	v_mfma_f32_32x32x16_bf16 v[16:31], v[198:201], v[224:227], v[16:31]
	v_sub_f32_e32 v230, v187, v231
	v_mul_f32_e32 v230, 0x3e0293ee, v230
	v_exp_f32_e32 v230, v230
	ds_read_b64_tr_b16 v[224:225], v174 offset:0x6600
	ds_read_b64_tr_b16 v[226:227], v174 offset:0x6e00
	v_mfma_f32_32x32x16_bf16 v[16:31], v[202:205], v[238:241], v[16:31]
	ds_read_b64_tr_b16 v[238:239], v174 offset:0x7600
	ds_read_b64_tr_b16 v[240:241], v174 offset:0x7e00
	s_waitcnt lgkmcnt(0)
	v_mfma_f32_32x32x16_bf16 v[0:15], v[146:149], v[208:211], v[0:15]
	v_mfma_f32_32x32x16_bf16 v[0:15], v[194:197], v[220:223], v[0:15]
	v_mfma_f32_32x32x16_bf16 v[0:15], v[198:201], v[224:227], v[0:15]
	v_mfma_f32_32x32x16_bf16 v[0:15], v[202:205], v[238:241], v[0:15]
	s_nop 0
	v_mov_b32_e32 v146, v230
	v_mov_b32_e32 v147, v231
	s_branch .Lpvj_1167b
.Lpvm_1167b:
	ds_read_b64_tr_b16 v[208:209], v174 offset:0x4000
	ds_read_b64_tr_b16 v[210:211], v174 offset:0x4800
	ds_read_b64_tr_b16 v[220:221], v174 offset:0x5000
	ds_read_b64_tr_b16 v[222:223], v174 offset:0x5800
	ds_read_b64_tr_b16 v[224:225], v174 offset:0x6000
	ds_read_b64_tr_b16 v[226:227], v174 offset:0x6800
	ds_read_b64_tr_b16 v[238:239], v174 offset:0x7000
	ds_read_b64_tr_b16 v[240:241], v174 offset:0x7800
	s_waitcnt lgkmcnt(0)
	s_nop 0
	v_mfma_f32_32x32x16_bf16 v[48:63], v[146:149], v[208:211], v[48:63]
	ds_read_b64_tr_b16 v[208:209], v174 offset:0x4200
	ds_read_b64_tr_b16 v[210:211], v174 offset:0x4a00
	v_mfma_f32_32x32x16_bf16 v[48:63], v[194:197], v[220:223], v[48:63]
	ds_read_b64_tr_b16 v[220:221], v174 offset:0x5200
	ds_read_b64_tr_b16 v[222:223], v174 offset:0x5a00
	v_mfma_f32_32x32x16_bf16 v[48:63], v[198:201], v[224:227], v[48:63]
	ds_read_b64_tr_b16 v[224:225], v174 offset:0x6200
	ds_read_b64_tr_b16 v[226:227], v174 offset:0x6a00
	v_mfma_f32_32x32x16_bf16 v[48:63], v[202:205], v[238:241], v[48:63]
	ds_read_b64_tr_b16 v[238:239], v174 offset:0x7200
	ds_read_b64_tr_b16 v[240:241], v174 offset:0x7a00
	s_waitcnt lgkmcnt(0)
	v_mfma_f32_32x32x16_bf16 v[32:47], v[146:149], v[208:211], v[32:47]
	ds_read_b64_tr_b16 v[208:209], v174 offset:0x4400
	ds_read_b64_tr_b16 v[210:211], v174 offset:0x4c00
	v_mfma_f32_32x32x16_bf16 v[32:47], v[194:197], v[220:223], v[32:47]
	ds_read_b64_tr_b16 v[220:221], v174 offset:0x5400
	ds_read_b64_tr_b16 v[222:223], v174 offset:0x5c00
	v_mfma_f32_32x32x16_bf16 v[32:47], v[198:201], v[224:227], v[32:47]
	ds_read_b64_tr_b16 v[224:225], v174 offset:0x6400
	ds_read_b64_tr_b16 v[226:227], v174 offset:0x6c00
	v_mfma_f32_32x32x16_bf16 v[32:47], v[202:205], v[238:241], v[32:47]
	ds_read_b64_tr_b16 v[238:239], v174 offset:0x7400
	ds_read_b64_tr_b16 v[240:241], v174 offset:0x7c00
	s_waitcnt lgkmcnt(0)
	v_mfma_f32_32x32x16_bf16 v[16:31], v[146:149], v[208:211], v[16:31]
	ds_read_b64_tr_b16 v[208:209], v174 offset:0x4600
	ds_read_b64_tr_b16 v[210:211], v174 offset:0x4e00
	v_mfma_f32_32x32x16_bf16 v[16:31], v[194:197], v[220:223], v[16:31]
	ds_read_b64_tr_b16 v[220:221], v174 offset:0x5600
	ds_read_b64_tr_b16 v[222:223], v174 offset:0x5e00
	v_mfma_f32_32x32x16_bf16 v[16:31], v[198:201], v[224:227], v[16:31]
	ds_read_b64_tr_b16 v[224:225], v174 offset:0x6600
	ds_read_b64_tr_b16 v[226:227], v174 offset:0x6e00
	v_mfma_f32_32x32x16_bf16 v[16:31], v[202:205], v[238:241], v[16:31]
	ds_read_b64_tr_b16 v[238:239], v174 offset:0x7600
	ds_read_b64_tr_b16 v[240:241], v174 offset:0x7e00
	s_waitcnt lgkmcnt(0)
	v_mfma_f32_32x32x16_bf16 v[0:15], v[146:149], v[208:211], v[0:15]
	s_cmp_le_i32 s92, s41
	v_mfma_f32_32x32x16_bf16 v[0:15], v[194:197], v[220:223], v[0:15]
	v_mfma_f32_32x32x16_bf16 v[0:15], v[198:201], v[224:227], v[0:15]
	v_mfma_f32_32x32x16_bf16 v[0:15], v[202:205], v[238:241], v[0:15]
	s_cbranch_scc1 .LBB0_1175
	v_cmp_gt_i32_e64 s[66:67], 26, v188
	v_cmp_gt_i32_e64 s[68:69], 27, v188
	v_cmp_gt_i32_e64 s[64:65], 25, v188
	s_and_b64 s[66:67], s[68:69], s[66:67]
	v_cmp_gt_i32_e64 s[62:63], 24, v188
	s_and_b64 s[64:65], s[66:67], s[64:65]
	v_cmp_gt_i32_e64 s[60:61], 19, v188
	s_and_b64 s[62:63], s[64:65], s[62:63]
	v_cmp_gt_i32_e64 s[58:59], 18, v188
	s_and_b64 s[60:61], s[62:63], s[60:61]
	v_cmp_gt_i32_e64 s[56:57], 17, v188
	s_and_b64 s[58:59], s[60:61], s[58:59]
	v_cmp_gt_i32_e64 s[54:55], 16, v188
	s_and_b64 s[56:57], s[58:59], s[56:57]
	v_cmp_gt_i32_e64 s[52:53], 11, v188
	s_and_b64 s[54:55], s[56:57], s[54:55]
	v_cmp_gt_i32_e64 s[50:51], 10, v188
	s_and_b64 s[52:53], s[54:55], s[52:53]
	v_cmp_gt_i32_e64 s[48:49], 9, v188
	s_and_b64 s[50:51], s[52:53], s[50:51]
	v_cmp_gt_i32_e64 s[46:47], 8, v188
	s_and_b64 s[48:49], s[50:51], s[48:49]
	v_cmp_gt_i32_e64 s[44:45], 3, v188
	s_and_b64 s[46:47], s[48:49], s[46:47]
	v_cmp_gt_i32_e64 s[42:43], 2, v188
	s_and_b64 s[44:45], s[46:47], s[44:45]
	v_cmp_gt_i32_e64 s[38:39], 1, v188
	s_and_b64 s[42:43], s[44:45], s[42:43]
	v_cmp_gt_i32_e64 s[36:37], 0, v188
	s_and_b64 s[38:39], s[42:43], s[38:39]
	s_and_b64 s[36:37], s[38:39], s[36:37]
	v_cmp_gt_i32_e64 s[34:35], 58, v188
	v_cndmask_b32_e64 v80, v80, v232, s[36:37]
	v_cmp_gt_i32_e64 s[36:37], 59, v188
	v_cmp_gt_i32_e64 s[30:31], 57, v188
	s_and_b64 s[34:35], s[36:37], s[34:35]
	v_cmp_gt_i32_e64 s[28:29], 56, v188
	s_and_b64 s[30:31], s[34:35], s[30:31]
	v_cmp_gt_i32_e64 s[26:27], 51, v188
	s_and_b64 s[28:29], s[30:31], s[28:29]
	v_cmp_gt_i32_e64 s[24:25], 50, v188
	s_and_b64 s[26:27], s[28:29], s[26:27]
	v_cmp_gt_i32_e64 s[22:23], 49, v188
	s_and_b64 s[24:25], s[26:27], s[24:25]
	v_cmp_gt_i32_e64 s[20:21], 48, v188
	s_and_b64 s[22:23], s[24:25], s[22:23]
	v_cmp_gt_i32_e64 s[18:19], 43, v188
	s_and_b64 s[20:21], s[22:23], s[20:21]
	v_cmp_gt_i32_e64 s[16:17], 42, v188
	s_and_b64 s[18:19], s[20:21], s[18:19]
	v_cmp_gt_i32_e64 s[14:15], 41, v188
	s_and_b64 s[16:17], s[18:19], s[16:17]
	v_cmp_gt_i32_e64 s[12:13], 40, v188
	s_and_b64 s[14:15], s[16:17], s[14:15]
	v_cmp_gt_i32_e64 s[10:11], 35, v188
	s_and_b64 s[12:13], s[14:15], s[12:13]
	v_cmp_gt_i32_e64 s[8:9], 34, v188
	s_and_b64 s[10:11], s[12:13], s[10:11]
	v_cmp_gt_i32_e64 s[6:7], 33, v188
	s_and_b64 s[8:9], s[10:11], s[8:9]
	v_cmp_gt_i32_e32 vcc, 32, v188
	s_and_b64 s[6:7], s[8:9], s[6:7]
	s_and_b64 vcc, s[6:7], vcc
	v_cndmask_b32_e64 v95, v95, v232, s[68:69]
	v_cndmask_b32_e64 v94, v94, v232, s[66:67]
	v_cndmask_b32_e64 v93, v93, v232, s[64:65]
	v_cndmask_b32_e64 v92, v92, v232, s[62:63]
	v_cndmask_b32_e64 v91, v91, v232, s[60:61]
	v_cndmask_b32_e64 v90, v90, v232, s[58:59]
	v_cndmask_b32_e64 v89, v89, v232, s[56:57]
	v_cndmask_b32_e64 v88, v88, v232, s[54:55]
	v_cndmask_b32_e64 v87, v87, v232, s[52:53]
	v_cndmask_b32_e64 v86, v86, v232, s[50:51]
	v_cndmask_b32_e64 v85, v85, v232, s[48:49]
	v_cndmask_b32_e64 v84, v84, v232, s[46:47]
	v_cndmask_b32_e64 v83, v83, v232, s[44:45]
	v_cndmask_b32_e64 v82, v82, v232, s[42:43]
	v_cndmask_b32_e64 v81, v81, v232, s[38:39]
	v_cndmask_b32_e64 v79, v79, v232, s[36:37]
	v_cndmask_b32_e64 v78, v78, v232, s[34:35]
	v_cndmask_b32_e64 v77, v77, v232, s[30:31]
	v_cndmask_b32_e64 v76, v76, v232, s[28:29]
	v_cndmask_b32_e64 v75, v75, v232, s[26:27]
	v_cndmask_b32_e64 v74, v74, v232, s[24:25]
	v_cndmask_b32_e64 v73, v73, v232, s[22:23]
	v_cndmask_b32_e64 v72, v72, v232, s[20:21]
	v_cndmask_b32_e64 v71, v71, v232, s[18:19]
	v_cndmask_b32_e64 v70, v70, v232, s[16:17]
	v_cndmask_b32_e64 v69, v69, v232, s[14:15]
	v_cndmask_b32_e64 v68, v68, v232, s[12:13]
	v_cndmask_b32_e64 v67, v67, v232, s[10:11]
	v_cndmask_b32_e64 v66, v66, v232, s[8:9]
	v_cndmask_b32_e64 v65, v65, v232, s[6:7]
	v_cndmask_b32_e32 v64, v64, v232, vcc

.Lpvj_1167b:
	s_cmp_eq_u64 vcc, exec
	s_cselect_b64 s[6:7], -1, 0
	s_barrier
	s_waitcnt vmcnt(0)
	v_cndmask_b32_e64 v146, v146, 1.0, s[6:7]
	v_cmp_gt_f32_e32 vcc, 1.0, v146
	s_waitcnt vmcnt(3)
	ds_write_b128 v184, v[130:133] offset:16384
	s_waitcnt vmcnt(2)
	ds_write_b128 v185, v[134:137] offset:16384
	s_waitcnt vmcnt(1)
	ds_write_b128 v176, v[138:141] offset:49152
	s_waitcnt vmcnt(0)
	ds_write_b128 v176, v[142:145] offset:57344
	s_cbranch_vccz .LBB0_1179
	s_and_saveexec_b64 s[8:9], s[4:5]
	ds_write_b32 v173, v146 offset:128
	s_or_b64 exec, exec, s[8:9]
	s_waitcnt lgkmcnt(0)
	ds_read_b128 v[130:133], v169 offset:224
	ds_read_b128 v[134:137], v169 offset:192
	ds_read_b128 v[138:141], v169 offset:160
	ds_read_b128 v[142:145], v169 offset:128
	s_waitcnt lgkmcnt(3)
	v_pk_mul_f32 v[62:63], v[62:63], v[132:133]
	s_waitcnt lgkmcnt(2)
	v_pk_mul_f32 v[58:59], v[58:59], v[136:137]
	s_waitcnt lgkmcnt(1)
	v_pk_mul_f32 v[54:55], v[54:55], v[140:141]
	s_waitcnt lgkmcnt(0)
	v_pk_mul_f32 v[50:51], v[50:51], v[144:145]
	v_pk_mul_f32 v[60:61], v[60:61], v[130:131]
	v_pk_mul_f32 v[56:57], v[56:57], v[134:135]
	v_pk_mul_f32 v[52:53], v[52:53], v[138:139]
	v_pk_mul_f32 v[48:49], v[48:49], v[142:143]
	v_pk_mul_f32 v[46:47], v[46:47], v[132:133]
	v_pk_mul_f32 v[42:43], v[42:43], v[136:137]
	v_pk_mul_f32 v[38:39], v[38:39], v[140:141]
	v_pk_mul_f32 v[34:35], v[34:35], v[144:145]
	v_pk_mul_f32 v[44:45], v[44:45], v[130:131]
	v_pk_mul_f32 v[40:41], v[40:41], v[134:135]
	v_pk_mul_f32 v[36:37], v[36:37], v[138:139]
	v_pk_mul_f32 v[32:33], v[32:33], v[142:143]
	v_pk_mul_f32 v[30:31], v[30:31], v[132:133]
	v_pk_mul_f32 v[26:27], v[26:27], v[136:137]
	v_pk_mul_f32 v[22:23], v[22:23], v[140:141]
	v_pk_mul_f32 v[18:19], v[18:19], v[144:145]
	v_pk_mul_f32 v[28:29], v[28:29], v[130:131]
	v_pk_mul_f32 v[24:25], v[24:25], v[134:135]
	v_pk_mul_f32 v[20:21], v[20:21], v[138:139]
	v_pk_mul_f32 v[16:17], v[16:17], v[142:143]
	v_pk_mul_f32 v[14:15], v[14:15], v[132:133]
	v_pk_mul_f32 v[10:11], v[10:11], v[136:137]
	v_pk_mul_f32 v[6:7], v[6:7], v[140:141]
	v_pk_mul_f32 v[2:3], v[2:3], v[144:145]
	v_pk_mul_f32 v[12:13], v[12:13], v[130:131]
	v_pk_mul_f32 v[8:9], v[8:9], v[134:135]
	v_pk_mul_f32 v[4:5], v[4:5], v[138:139]
	v_pk_mul_f32 v[0:1], v[0:1], v[142:143]

.LBB0_1354:
	ds_read_b128 v[80:83], v193
	ds_read_b128 v[84:87], v193 offset:32
	ds_read_b128 v[64:67], v193 offset:128
	ds_read_b128 v[68:71], v193 offset:160
	ds_read_b128 v[88:91], v193 offset:64
	ds_read_b128 v[72:75], v193 offset:192
	ds_read_b128 v[92:95], v193 offset:96
	ds_read_b128 v[76:79], v193 offset:224
	ds_read_b128 v[130:133], v187 offset:49152
	s_waitcnt vmcnt(2)
	ds_read_b128 v[134:137], v187 offset:57344
	s_waitcnt vmcnt(1)
	v_exp_f32_e32 v138, v146
	v_add_f32_e32 v146, 0, v203
	v_add_f32_e32 v146, v204, v146
	s_waitcnt lgkmcnt(1)
	v_mfma_f32_32x32x16_bf16 v[80:95], v[130:133], v[126:129], v[80:95]
	v_add_f32_e32 v146, v205, v146
	v_add_f32_e32 v146, v207, v146
	v_add_f32_e32 v146, v208, v146
	v_add_f32_e32 v146, v210, v146
	v_add_f32_e32 v146, v206, v146
	v_add_f32_e32 v146, v209, v146
	v_add_f32_e32 v146, v173, v146
	s_waitcnt lgkmcnt(0)
	v_mfma_f32_32x32x16_bf16 v[64:79], v[134:137], v[126:129], v[64:79]
	ds_read_b128 v[130:133], v188 offset:49152
	ds_read_b128 v[134:137], v188 offset:57344
	v_add_f32_e32 v146, v175, v146
	v_add_f32_e32 v146, v198, v146
	v_add_f32_e32 v146, v201, v146
	v_add_f32_e32 v146, v174, v146
	v_add_f32_e32 v146, v199, v146
	v_add_f32_e32 v146, v200, v146
	s_waitcnt lgkmcnt(1)
	v_mfma_f32_32x32x16_bf16 v[80:95], v[130:133], v[122:125], v[80:95]
	v_add_f32_e32 v146, v202, v146
	v_exp_f32_e32 v139, v147
	v_exp_f32_e32 v140, v160
	v_exp_f32_e32 v141, v161
	s_waitcnt vmcnt(0)
	v_exp_f32_e32 v142, v154
	v_exp_f32_e32 v143, v155
	v_exp_f32_e32 v144, v148
	s_waitcnt lgkmcnt(0)
	v_mfma_f32_32x32x16_bf16 v[64:79], v[134:137], v[122:125], v[64:79]
	ds_read_b128 v[130:133], v186 offset:49152
	ds_read_b128 v[134:137], v186 offset:57344
	v_exp_f32_e32 v145, v149
	v_cvt_pk_bf16_f32 v147, v205, v207
	v_cvt_pk_bf16_f32 v148, v208, v210
	v_cvt_pk_bf16_f32 v149, v206, v209
	v_cvt_pk_bf16_f32 v160, v142, v143
	v_cvt_pk_bf16_f32 v161, v144, v145
	s_waitcnt lgkmcnt(1)
	v_mfma_f32_32x32x16_bf16 v[80:95], v[130:133], v[118:121], v[80:95]
	v_permlane32_swap_b32_e32 v147, v149
	s_waitcnt lgkmcnt(0)
	v_mfma_f32_32x32x16_bf16 v[64:79], v[134:137], v[118:121], v[64:79]
	ds_read_b128 v[130:133], v167 offset:49152
	ds_read_b128 v[134:137], v167 offset:57344
	s_waitcnt lgkmcnt(1)
	v_mfma_f32_32x32x16_bf16 v[80:95], v[130:133], v[114:117], v[80:95]
	s_waitcnt lgkmcnt(0)
	v_mfma_f32_32x32x16_bf16 v[64:79], v[134:137], v[114:117], v[64:79]
	ds_read_b128 v[130:133], v187 offset:49280
	ds_read_b128 v[134:137], v187 offset:57472
	s_waitcnt lgkmcnt(1)
	v_mfma_f32_32x32x16_bf16 v[80:95], v[130:133], v[110:113], v[80:95]
	s_waitcnt lgkmcnt(0)
	v_mfma_f32_32x32x16_bf16 v[64:79], v[134:137], v[110:113], v[64:79]
	ds_read_b128 v[130:133], v188 offset:49280
	ds_read_b128 v[134:137], v188 offset:57472
	s_waitcnt lgkmcnt(1)
	v_mfma_f32_32x32x16_bf16 v[80:95], v[130:133], v[106:109], v[80:95]
	s_waitcnt lgkmcnt(0)
	v_mfma_f32_32x32x16_bf16 v[64:79], v[134:137], v[106:109], v[64:79]
	ds_read_b128 v[130:133], v186 offset:49280
	ds_read_b128 v[134:137], v186 offset:57472
	s_waitcnt lgkmcnt(1)
	v_mfma_f32_32x32x16_bf16 v[80:95], v[130:133], v[102:105], v[80:95]
	s_waitcnt lgkmcnt(0)
	v_mfma_f32_32x32x16_bf16 v[64:79], v[134:137], v[102:105], v[64:79]
	ds_read_b128 v[130:133], v167 offset:49280
	ds_read_b128 v[134:137], v167 offset:57472
	s_waitcnt lgkmcnt(1)
	v_mfma_f32_32x32x16_bf16 v[80:95], v[130:133], v[98:101], v[80:95]
	v_exp_f32_e32 v130, v158
	v_exp_f32_e32 v131, v159
	v_exp_f32_e32 v132, v156
	v_exp_f32_e32 v133, v157
	v_add_f32_e32 v146, v130, v146
	v_add_f32_e32 v146, v131, v146
	v_add_f32_e32 v146, v132, v146
	s_waitcnt lgkmcnt(0)
	v_mfma_f32_32x32x16_bf16 v[64:79], v[134:137], v[98:101], v[64:79]
	v_exp_f32_e32 v134, v152
	v_exp_f32_e32 v135, v153
	v_exp_f32_e32 v136, v150
	v_exp_f32_e32 v137, v151
	v_add_f32_e32 v146, v133, v146
	v_add_f32_e32 v146, v134, v146
	v_add_f32_e32 v146, v135, v146
	v_add_f32_e32 v146, v136, v146
	v_add_f32_e32 v146, v137, v146
	v_add_f32_e32 v146, v138, v146
	v_add_f32_e32 v146, v139, v146
	v_add_f32_e32 v146, v140, v146
	v_add_f32_e32 v146, v141, v146
	v_add_f32_e32 v146, v142, v146
	v_add_f32_e32 v146, v143, v146
	v_add_f32_e32 v146, v144, v146
	v_add_f32_e32 v195, v145, v146
	v_mov_b32_e32 v196, v195
	s_nop 1
	v_permlane32_swap_b32_e32 v195, v196
	v_cvt_pk_bf16_f32 v146, v203, v204
	v_cvt_pk_bf16_f32 v150, v173, v175
	v_cvt_pk_bf16_f32 v151, v198, v201
	v_cvt_pk_bf16_f32 v152, v174, v199
	v_cvt_pk_bf16_f32 v153, v200, v202
	v_cvt_pk_bf16_f32 v154, v130, v131
	v_cvt_pk_bf16_f32 v155, v132, v133
	v_cvt_pk_bf16_f32 v156, v134, v135
	v_cvt_pk_bf16_f32 v157, v136, v137
	v_cvt_pk_bf16_f32 v158, v138, v139
	v_cvt_pk_bf16_f32 v159, v140, v141
	v_permlane32_swap_b32_e32 v146, v148
	v_permlane32_swap_b32_e32 v150, v152
	v_permlane32_swap_b32_e32 v151, v153
	v_permlane32_swap_b32_e32 v154, v156
	v_permlane32_swap_b32_e32 v155, v157
	v_permlane32_swap_b32_e32 v158, v160
	v_permlane32_swap_b32_e32 v159, v161
	v_lshl_add_u64 v[174:175], v[168:169], 0, v[96:97]
	s_mov_b32 s6, 0x15c40000
	v_add_co_u32_e32 v130, vcc, s6, v174
	s_mov_b32 s6, 0x15c50000
	s_nop 0
	v_addc_co_u32_e32 v131, vcc, 0, v175, vcc
	v_add_co_u32_e32 v134, vcc, s6, v174
	v_lshl_add_u64 v[172:173], v[170:171], 0, v[96:97]
	s_nop 0
	v_addc_co_u32_e32 v135, vcc, 0, v175, vcc
	s_mov_b32 s6, 0x14b40000
	v_add_co_u32_e32 v138, vcc, s6, v172
	s_mov_b32 s6, 0x14b50000
	s_nop 0
	v_addc_co_u32_e32 v139, vcc, 0, v173, vcc
	v_add_co_u32_e32 v142, vcc, s6, v172
	global_load_dwordx4 v[130:133], v[130:131], off
	s_nop 0
	global_load_dwordx4 v[134:137], v[134:135], off
	v_addc_co_u32_e32 v143, vcc, 0, v173, vcc
	global_load_dwordx4 v[138:141], v[138:139], off
	s_nop 0
	global_load_dwordx4 v[142:145], v[142:143], off
	s_sub_i32 s6, s92, 64
	s_cmp_le_i32 s6, s41
	s_cbranch_scc0 .Lpvm_1354a
	ds_read_b64_tr_b16 v[198:199], v180 offset:0
	ds_read_b64_tr_b16 v[200:201], v180 offset:0x800
	ds_read_b64_tr_b16 v[202:203], v180 offset:0x1000
	ds_read_b64_tr_b16 v[204:205], v180 offset:0x1800
	ds_read_b64_tr_b16 v[206:207], v180 offset:0x2000
	ds_read_b64_tr_b16 v[208:209], v180 offset:0x2800
	ds_read_b64_tr_b16 v[210:211], v180 offset:0x3000
	ds_read_b64_tr_b16 v[212:213], v180 offset:0x3800
	s_waitcnt lgkmcnt(0)
	s_nop 0
	v_mfma_f32_32x32x16_bf16 v[48:63], v[146:149], v[198:201], v[48:63]
	v_max_f32_e32 v230, v81, v81
	v_max_f32_e32 v231, v80, v80
	v_max_f32_e32 v230, v231, v230
	ds_read_b64_tr_b16 v[198:199], v180 offset:0x200
	ds_read_b64_tr_b16 v[200:201], v180 offset:0xa00
	v_mfma_f32_32x32x16_bf16 v[48:63], v[150:153], v[202:205], v[48:63]
	v_max3_f32 v230, v230, v82, v83
	v_max3_f32 v230, v230, v84, v85
	v_max3_f32 v230, v230, v86, v87
	ds_read_b64_tr_b16 v[202:203], v180 offset:0x1200
	ds_read_b64_tr_b16 v[204:205], v180 offset:0x1a00
	v_mfma_f32_32x32x16_bf16 v[48:63], v[154:157], v[206:209], v[48:63]
	v_max3_f32 v230, v230, v88, v89
	v_max3_f32 v230, v230, v90, v91
	v_max3_f32 v230, v230, v92, v93
	ds_read_b64_tr_b16 v[206:207], v180 offset:0x2200
	ds_read_b64_tr_b16 v[208:209], v180 offset:0x2a00
	v_mfma_f32_32x32x16_bf16 v[48:63], v[158:161], v[210:213], v[48:63]
	v_max3_f32 v230, v230, v94, v95
	v_max3_f32 v230, v230, v64, v65
	v_max3_f32 v230, v230, v66, v67
	ds_read_b64_tr_b16 v[210:211], v180 offset:0x3200
	ds_read_b64_tr_b16 v[212:213], v180 offset:0x3a00
	s_waitcnt lgkmcnt(0)
	v_mfma_f32_32x32x16_bf16 v[32:47], v[146:149], v[198:201], v[32:47]
	v_max3_f32 v230, v230, v68, v69
	v_max3_f32 v230, v230, v70, v71
	v_max3_f32 v230, v230, v72, v73
	ds_read_b64_tr_b16 v[198:199], v180 offset:0x400
	ds_read_b64_tr_b16 v[200:201], v180 offset:0xc00
	v_mfma_f32_32x32x16_bf16 v[32:47], v[150:153], v[202:205], v[32:47]
	v_max3_f32 v230, v230, v74, v75
	v_max3_f32 v230, v230, v76, v77
	v_max3_f32 v230, v230, v78, v79
	ds_read_b64_tr_b16 v[202:203], v180 offset:0x1400
	ds_read_b64_tr_b16 v[204:205], v180 offset:0x1c00
	v_mfma_f32_32x32x16_bf16 v[32:47], v[154:157], v[206:209], v[32:47]
	v_mov_b32_e32 v231, v230
	s_nop 1
	v_permlane32_swap_b32_e32 v230, v231
	ds_read_b64_tr_b16 v[206:207], v180 offset:0x2400
	ds_read_b64_tr_b16 v[208:209], v180 offset:0x2c00
	v_mfma_f32_32x32x16_bf16 v[32:47], v[158:161], v[210:213], v[32:47]
	v_max_f32_e32 v231, v231, v231
	v_max_f32_e32 v230, v230, v230
	v_max_f32_e32 v230, v230, v231
	ds_read_b64_tr_b16 v[210:211], v180 offset:0x3400
	ds_read_b64_tr_b16 v[212:213], v180 offset:0x3c00
	s_waitcnt lgkmcnt(0)
	v_mfma_f32_32x32x16_bf16 v[16:31], v[146:149], v[198:201], v[16:31]
	v_sub_f32_e32 v231, v230, v194
	v_mul_f32_e32 v231, 0x3db504f3, v231
	s_mov_b32 s6, 0x41000000
	ds_read_b64_tr_b16 v[198:199], v180 offset:0x600
	ds_read_b64_tr_b16 v[200:201], v180 offset:0xe00
	v_mfma_f32_32x32x16_bf16 v[16:31], v[150:153], v[202:205], v[16:31]
	v_cmp_ge_f32_e32 vcc, s6, v231
	v_max_f32_e32 v231, v194, v194
	v_max_f32_e32 v230, v231, v230
	ds_read_b64_tr_b16 v[202:203], v180 offset:0x1600
	ds_read_b64_tr_b16 v[204:205], v180 offset:0x1e00
	v_mfma_f32_32x32x16_bf16 v[16:31], v[154:157], v[206:209], v[16:31]
	v_sub_f32_e32 v231, v194, v230
	v_mul_f32_e32 v231, 0x3e0293ee, v231
	v_exp_f32_e32 v231, v231
	ds_read_b64_tr_b16 v[206:207], v180 offset:0x2600
	ds_read_b64_tr_b16 v[208:209], v180 offset:0x2e00
	v_mfma_f32_32x32x16_bf16 v[16:31], v[158:161], v[210:213], v[16:31]
	ds_read_b64_tr_b16 v[210:211], v180 offset:0x3600
	ds_read_b64_tr_b16 v[212:213], v180 offset:0x3e00
	s_waitcnt lgkmcnt(0)
	v_mfma_f32_32x32x16_bf16 v[0:15], v[146:149], v[198:201], v[0:15]
	v_mfma_f32_32x32x16_bf16 v[0:15], v[150:153], v[202:205], v[0:15]
	v_mfma_f32_32x32x16_bf16 v[0:15], v[154:157], v[206:209], v[0:15]
	v_mfma_f32_32x32x16_bf16 v[0:15], v[158:161], v[210:213], v[0:15]
	s_nop 0
	v_mov_b32_e32 v146, v230
	v_mov_b32_e32 v147, v231
	s_branch .Lpvj_1354a
.Lpvm_1354a:
	ds_read_b64_tr_b16 v[198:199], v180 offset:0
	ds_read_b64_tr_b16 v[200:201], v180 offset:0x800
	ds_read_b64_tr_b16 v[202:203], v180 offset:0x1000
	ds_read_b64_tr_b16 v[204:205], v180 offset:0x1800
	ds_read_b64_tr_b16 v[206:207], v180 offset:0x2000
	ds_read_b64_tr_b16 v[208:209], v180 offset:0x2800
	ds_read_b64_tr_b16 v[210:211], v180 offset:0x3000
	ds_read_b64_tr_b16 v[212:213], v180 offset:0x3800
	s_waitcnt lgkmcnt(0)
	s_nop 0
	v_mfma_f32_32x32x16_bf16 v[48:63], v[146:149], v[198:201], v[48:63]
	ds_read_b64_tr_b16 v[198:199], v180 offset:0x200
	ds_read_b64_tr_b16 v[200:201], v180 offset:0xa00
	v_mfma_f32_32x32x16_bf16 v[48:63], v[150:153], v[202:205], v[48:63]
	ds_read_b64_tr_b16 v[202:203], v180 offset:0x1200
	ds_read_b64_tr_b16 v[204:205], v180 offset:0x1a00
	v_mfma_f32_32x32x16_bf16 v[48:63], v[154:157], v[206:209], v[48:63]
	ds_read_b64_tr_b16 v[206:207], v180 offset:0x2200
	ds_read_b64_tr_b16 v[208:209], v180 offset:0x2a00
	v_mfma_f32_32x32x16_bf16 v[48:63], v[158:161], v[210:213], v[48:63]
	ds_read_b64_tr_b16 v[210:211], v180 offset:0x3200
	ds_read_b64_tr_b16 v[212:213], v180 offset:0x3a00
	s_waitcnt lgkmcnt(0)
	v_mfma_f32_32x32x16_bf16 v[32:47], v[146:149], v[198:201], v[32:47]
	ds_read_b64_tr_b16 v[198:199], v180 offset:0x400
	ds_read_b64_tr_b16 v[200:201], v180 offset:0xc00
	v_mfma_f32_32x32x16_bf16 v[32:47], v[150:153], v[202:205], v[32:47]
	ds_read_b64_tr_b16 v[202:203], v180 offset:0x1400
	ds_read_b64_tr_b16 v[204:205], v180 offset:0x1c00
	v_mfma_f32_32x32x16_bf16 v[32:47], v[154:157], v[206:209], v[32:47]
	ds_read_b64_tr_b16 v[206:207], v180 offset:0x2400
	ds_read_b64_tr_b16 v[208:209], v180 offset:0x2c00
	v_mfma_f32_32x32x16_bf16 v[32:47], v[158:161], v[210:213], v[32:47]
	ds_read_b64_tr_b16 v[210:211], v180 offset:0x3400
	ds_read_b64_tr_b16 v[212:213], v180 offset:0x3c00
	s_waitcnt lgkmcnt(0)
	v_mfma_f32_32x32x16_bf16 v[16:31], v[146:149], v[198:201], v[16:31]
	ds_read_b64_tr_b16 v[198:199], v180 offset:0x600
	ds_read_b64_tr_b16 v[200:201], v180 offset:0xe00
	v_mfma_f32_32x32x16_bf16 v[16:31], v[150:153], v[202:205], v[16:31]
	ds_read_b64_tr_b16 v[202:203], v180 offset:0x1600
	ds_read_b64_tr_b16 v[204:205], v180 offset:0x1e00
	v_mfma_f32_32x32x16_bf16 v[16:31], v[154:157], v[206:209], v[16:31]
	ds_read_b64_tr_b16 v[206:207], v180 offset:0x2600
	ds_read_b64_tr_b16 v[208:209], v180 offset:0x2e00
	v_mfma_f32_32x32x16_bf16 v[16:31], v[158:161], v[210:213], v[16:31]
	ds_read_b64_tr_b16 v[210:211], v180 offset:0x3600
	ds_read_b64_tr_b16 v[212:213], v180 offset:0x3e00
	s_waitcnt lgkmcnt(0)
	v_mfma_f32_32x32x16_bf16 v[0:15], v[146:149], v[198:201], v[0:15]
	s_sub_i32 s6, s92, 64
	s_cmp_le_i32 s6, s41
	v_mfma_f32_32x32x16_bf16 v[0:15], v[150:153], v[202:205], v[0:15]
	v_mfma_f32_32x32x16_bf16 v[0:15], v[154:157], v[206:209], v[0:15]
	v_mfma_f32_32x32x16_bf16 v[0:15], v[158:161], v[210:213], v[0:15]
	s_cbranch_scc1 .LBB0_1356
	v_add_u32_e32 v146, 64, v192
	v_cmp_gt_i32_e64 s[66:67], 26, v146
	v_cmp_gt_i32_e64 s[68:69], 27, v146
	v_cmp_gt_i32_e64 s[64:65], 25, v146
	s_and_b64 s[66:67], s[68:69], s[66:67]
	v_cmp_gt_i32_e64 s[62:63], 24, v146
	s_and_b64 s[64:65], s[66:67], s[64:65]
	v_cmp_gt_i32_e64 s[60:61], 19, v146
	s_and_b64 s[62:63], s[64:65], s[62:63]
	v_cmp_gt_i32_e64 s[58:59], 18, v146
	s_and_b64 s[60:61], s[62:63], s[60:61]
	v_cmp_gt_i32_e64 s[56:57], 17, v146
	s_and_b64 s[58:59], s[60:61], s[58:59]
	v_cmp_gt_i32_e64 s[54:55], 16, v146
	s_and_b64 s[56:57], s[58:59], s[56:57]
	v_cmp_gt_i32_e64 s[52:53], 11, v146
	s_and_b64 s[54:55], s[56:57], s[54:55]
	v_cmp_gt_i32_e64 s[50:51], 10, v146
	s_and_b64 s[52:53], s[54:55], s[52:53]
	v_cmp_gt_i32_e64 s[48:49], 9, v146
	s_and_b64 s[50:51], s[52:53], s[50:51]
	v_cmp_gt_i32_e64 s[46:47], 8, v146
	s_and_b64 s[48:49], s[50:51], s[48:49]
	v_cmp_gt_i32_e64 s[44:45], 3, v146
	s_and_b64 s[46:47], s[48:49], s[46:47]
	v_cmp_gt_i32_e64 s[42:43], 2, v146
	s_and_b64 s[44:45], s[46:47], s[44:45]
	v_cmp_gt_i32_e64 s[38:39], 1, v146
	s_and_b64 s[42:43], s[44:45], s[42:43]
	v_cmp_gt_i32_e64 s[36:37], 0, v146
	s_and_b64 s[38:39], s[42:43], s[38:39]
	s_and_b64 s[36:37], s[38:39], s[36:37]
	v_cmp_gt_i32_e64 s[34:35], 58, v146
	v_cndmask_b32_e64 v80, v80, v232, s[36:37]
	v_cmp_gt_i32_e64 s[36:37], 59, v146
	v_cmp_gt_i32_e64 s[30:31], 57, v146
	s_and_b64 s[34:35], s[36:37], s[34:35]
	v_cmp_gt_i32_e64 s[28:29], 56, v146
	s_and_b64 s[30:31], s[34:35], s[30:31]
	v_cmp_gt_i32_e64 s[26:27], 51, v146
	s_and_b64 s[28:29], s[30:31], s[28:29]
	v_cmp_gt_i32_e64 s[24:25], 50, v146
	s_and_b64 s[26:27], s[28:29], s[26:27]
	v_cmp_gt_i32_e64 s[22:23], 49, v146
	s_and_b64 s[24:25], s[26:27], s[24:25]
	v_cmp_gt_i32_e64 s[20:21], 48, v146
	s_and_b64 s[22:23], s[24:25], s[22:23]
	v_cmp_gt_i32_e64 s[18:19], 43, v146
	s_and_b64 s[20:21], s[22:23], s[20:21]
	v_cmp_gt_i32_e64 s[16:17], 42, v146
	s_and_b64 s[18:19], s[20:21], s[18:19]
	v_cmp_gt_i32_e64 s[14:15], 41, v146
	s_and_b64 s[16:17], s[18:19], s[16:17]
	v_cmp_gt_i32_e64 s[12:13], 40, v146
	s_and_b64 s[14:15], s[16:17], s[14:15]
	v_cmp_gt_i32_e64 s[10:11], 35, v146
	s_and_b64 s[12:13], s[14:15], s[12:13]
	v_cmp_gt_i32_e64 s[8:9], 34, v146
	s_and_b64 s[10:11], s[12:13], s[10:11]
	v_cmp_gt_i32_e64 s[6:7], 33, v146
	s_and_b64 s[8:9], s[10:11], s[8:9]
	v_cmp_gt_i32_e32 vcc, 32, v146
	s_and_b64 s[6:7], s[8:9], s[6:7]
	s_and_b64 vcc, s[6:7], vcc
	v_cndmask_b32_e64 v95, v95, v232, s[68:69]
	v_cndmask_b32_e64 v94, v94, v232, s[66:67]
	v_cndmask_b32_e64 v93, v93, v232, s[64:65]
	v_cndmask_b32_e64 v92, v92, v232, s[62:63]
	v_cndmask_b32_e64 v91, v91, v232, s[60:61]
	v_cndmask_b32_e64 v90, v90, v232, s[58:59]
	v_cndmask_b32_e64 v89, v89, v232, s[56:57]
	v_cndmask_b32_e64 v88, v88, v232, s[54:55]
	v_cndmask_b32_e64 v87, v87, v232, s[52:53]
	v_cndmask_b32_e64 v86, v86, v232, s[50:51]
	v_cndmask_b32_e64 v85, v85, v232, s[48:49]
	v_cndmask_b32_e64 v84, v84, v232, s[46:47]
	v_cndmask_b32_e64 v83, v83, v232, s[44:45]
	v_cndmask_b32_e64 v82, v82, v232, s[42:43]
	v_cndmask_b32_e64 v81, v81, v232, s[38:39]
	v_cndmask_b32_e64 v79, v79, v232, s[36:37]
	v_cndmask_b32_e64 v78, v78, v232, s[34:35]
	v_cndmask_b32_e64 v77, v77, v232, s[30:31]
	v_cndmask_b32_e64 v76, v76, v232, s[28:29]
	v_cndmask_b32_e64 v75, v75, v232, s[26:27]
	v_cndmask_b32_e64 v74, v74, v232, s[24:25]
	v_cndmask_b32_e64 v73, v73, v232, s[22:23]
	v_cndmask_b32_e64 v72, v72, v232, s[20:21]
	v_cndmask_b32_e64 v71, v71, v232, s[18:19]
	v_cndmask_b32_e64 v70, v70, v232, s[16:17]
	v_cndmask_b32_e64 v69, v69, v232, s[14:15]
	v_cndmask_b32_e64 v68, v68, v232, s[12:13]
	v_cndmask_b32_e64 v67, v67, v232, s[10:11]
	v_cndmask_b32_e64 v66, v66, v232, s[8:9]
	v_cndmask_b32_e64 v65, v65, v232, s[6:7]
	v_cndmask_b32_e32 v64, v64, v232, vcc

.Lpvj_1354a:
	s_cmp_eq_u64 vcc, exec
	s_cselect_b64 s[6:7], -1, 0
	s_barrier
	s_waitcnt vmcnt(0)
	v_cndmask_b32_e64 v197, v147, 1.0, s[6:7]
	v_cmp_gt_f32_e32 vcc, 1.0, v197
	s_waitcnt vmcnt(3)
	ds_write_b128 v189, v[130:133]
	s_waitcnt vmcnt(2)
	ds_write_b128 v190, v[134:137]
	s_waitcnt vmcnt(1)
	ds_write_b128 v183, v[138:141] offset:32768
	s_waitcnt vmcnt(0)
	ds_write_b128 v183, v[142:145] offset:40960
	s_cbranch_vccz .LBB0_1360
	s_and_saveexec_b64 s[8:9], s[4:5]
	ds_write_b32 v182, v197 offset:128
	s_or_b64 exec, exec, s[8:9]
	s_waitcnt lgkmcnt(0)
	ds_read_b128 v[148:151], v165 offset:224
	ds_read_b128 v[152:155], v165 offset:192
	ds_read_b128 v[156:159], v165 offset:160
	ds_read_b128 v[198:201], v165 offset:128
	s_waitcnt lgkmcnt(3)
	v_pk_mul_f32 v[62:63], v[62:63], v[150:151]
	s_waitcnt lgkmcnt(2)
	v_pk_mul_f32 v[58:59], v[58:59], v[154:155]
	s_waitcnt lgkmcnt(1)
	v_pk_mul_f32 v[54:55], v[54:55], v[158:159]
	s_waitcnt lgkmcnt(0)
	v_pk_mul_f32 v[50:51], v[50:51], v[200:201]
	v_pk_mul_f32 v[60:61], v[60:61], v[148:149]
	v_pk_mul_f32 v[56:57], v[56:57], v[152:153]
	v_pk_mul_f32 v[52:53], v[52:53], v[156:157]
	v_pk_mul_f32 v[48:49], v[48:49], v[198:199]
	v_pk_mul_f32 v[46:47], v[46:47], v[150:151]
	v_pk_mul_f32 v[42:43], v[42:43], v[154:155]
	v_pk_mul_f32 v[38:39], v[38:39], v[158:159]
	v_pk_mul_f32 v[34:35], v[34:35], v[200:201]
	v_pk_mul_f32 v[44:45], v[44:45], v[148:149]
	v_pk_mul_f32 v[40:41], v[40:41], v[152:153]
	v_pk_mul_f32 v[36:37], v[36:37], v[156:157]
	v_pk_mul_f32 v[32:33], v[32:33], v[198:199]
	v_pk_mul_f32 v[30:31], v[30:31], v[150:151]
	v_pk_mul_f32 v[26:27], v[26:27], v[154:155]
	v_pk_mul_f32 v[22:23], v[22:23], v[158:159]
	v_pk_mul_f32 v[18:19], v[18:19], v[200:201]
	v_pk_mul_f32 v[28:29], v[28:29], v[148:149]
	v_pk_mul_f32 v[24:25], v[24:25], v[152:153]
	v_pk_mul_f32 v[20:21], v[20:21], v[156:157]
	v_pk_mul_f32 v[16:17], v[16:17], v[198:199]
	v_pk_mul_f32 v[14:15], v[14:15], v[150:151]
	v_pk_mul_f32 v[10:11], v[10:11], v[154:155]
	v_pk_mul_f32 v[6:7], v[6:7], v[158:159]
	v_pk_mul_f32 v[2:3], v[2:3], v[200:201]
	v_pk_mul_f32 v[12:13], v[12:13], v[148:149]
	v_pk_mul_f32 v[8:9], v[8:9], v[152:153]
	v_pk_mul_f32 v[4:5], v[4:5], v[156:157]
	v_pk_mul_f32 v[0:1], v[0:1], v[198:199]

.LBB0_1362:
	s_cmp_le_i32 s92, s41
	s_cbranch_scc0 .Lpvm_1354b
	ds_read_b64_tr_b16 v[172:173], v180 offset:0x4000
	ds_read_b64_tr_b16 v[174:175], v180 offset:0x4800
	ds_read_b64_tr_b16 v[198:199], v180 offset:0x5000
	ds_read_b64_tr_b16 v[200:201], v180 offset:0x5800
	ds_read_b64_tr_b16 v[202:203], v180 offset:0x6000
	ds_read_b64_tr_b16 v[204:205], v180 offset:0x6800
	ds_read_b64_tr_b16 v[206:207], v180 offset:0x7000
	ds_read_b64_tr_b16 v[208:209], v180 offset:0x7800
	s_waitcnt lgkmcnt(0)
	s_nop 0
	v_mfma_f32_32x32x16_bf16 v[48:63], v[146:149], v[172:175], v[48:63]
	v_max_f32_e32 v230, v81, v81
	v_max_f32_e32 v231, v80, v80
	ds_read_b64_tr_b16 v[172:173], v180 offset:0x4200
	ds_read_b64_tr_b16 v[174:175], v180 offset:0x4a00
	v_mfma_f32_32x32x16_bf16 v[48:63], v[150:153], v[198:201], v[48:63]
	v_max_f32_e32 v230, v231, v230
	v_max3_f32 v230, v230, v82, v83
	ds_read_b64_tr_b16 v[198:199], v180 offset:0x5200
	ds_read_b64_tr_b16 v[200:201], v180 offset:0x5a00
	v_mfma_f32_32x32x16_bf16 v[48:63], v[154:157], v[202:205], v[48:63]
	v_max3_f32 v230, v230, v84, v85
	v_max3_f32 v230, v230, v86, v87
	ds_read_b64_tr_b16 v[202:203], v180 offset:0x6200
	ds_read_b64_tr_b16 v[204:205], v180 offset:0x6a00
	v_mfma_f32_32x32x16_bf16 v[48:63], v[158:161], v[206:209], v[48:63]
	v_max3_f32 v230, v230, v88, v89
	v_max3_f32 v230, v230, v90, v91
	ds_read_b64_tr_b16 v[206:207], v180 offset:0x7200
	ds_read_b64_tr_b16 v[208:209], v180 offset:0x7a00
	s_waitcnt lgkmcnt(0)
	v_mfma_f32_32x32x16_bf16 v[32:47], v[146:149], v[172:175], v[32:47]
	v_max3_f32 v230, v230, v92, v93
	v_max3_f32 v230, v230, v94, v95
	ds_read_b64_tr_b16 v[172:173], v180 offset:0x4400
	ds_read_b64_tr_b16 v[174:175], v180 offset:0x4c00
	v_mfma_f32_32x32x16_bf16 v[32:47], v[150:153], v[198:201], v[32:47]
	v_max3_f32 v230, v230, v64, v65
	v_max3_f32 v230, v230, v66, v67
	ds_read_b64_tr_b16 v[198:199], v180 offset:0x5400
	ds_read_b64_tr_b16 v[200:201], v180 offset:0x5c00
	v_mfma_f32_32x32x16_bf16 v[32:47], v[154:157], v[202:205], v[32:47]
	v_max3_f32 v230, v230, v68, v69
	v_max3_f32 v230, v230, v70, v71
	ds_read_b64_tr_b16 v[202:203], v180 offset:0x6400
	ds_read_b64_tr_b16 v[204:205], v180 offset:0x6c00
	v_mfma_f32_32x32x16_bf16 v[32:47], v[158:161], v[206:209], v[32:47]
	v_max3_f32 v230, v230, v72, v73
	v_max3_f32 v230, v230, v74, v75
	ds_read_b64_tr_b16 v[206:207], v180 offset:0x7400
	ds_read_b64_tr_b16 v[208:209], v180 offset:0x7c00
	s_waitcnt lgkmcnt(0)
	v_mfma_f32_32x32x16_bf16 v[16:31], v[146:149], v[172:175], v[16:31]
	v_max3_f32 v230, v230, v76, v77
	v_max3_f32 v230, v230, v78, v79
	ds_read_b64_tr_b16 v[172:173], v180 offset:0x4600
	ds_read_b64_tr_b16 v[174:175], v180 offset:0x4e00
	v_mfma_f32_32x32x16_bf16 v[16:31], v[150:153], v[198:201], v[16:31]
	v_mov_b32_e32 v231, v230
	s_nop 1
	ds_read_b64_tr_b16 v[198:199], v180 offset:0x5600
	ds_read_b64_tr_b16 v[200:201], v180 offset:0x5e00
	v_mfma_f32_32x32x16_bf16 v[16:31], v[154:157], v[202:205], v[16:31]
	v_permlane32_swap_b32_e32 v230, v231
	v_max_f32_e32 v231, v231, v231
	ds_read_b64_tr_b16 v[202:203], v180 offset:0x6600
	ds_read_b64_tr_b16 v[204:205], v180 offset:0x6e00
	v_mfma_f32_32x32x16_bf16 v[16:31], v[158:161], v[206:209], v[16:31]
	v_max_f32_e32 v230, v230, v230
	v_max_f32_e32 v230, v230, v231
	ds_read_b64_tr_b16 v[206:207], v180 offset:0x7600
	ds_read_b64_tr_b16 v[208:209], v180 offset:0x7e00
	s_waitcnt lgkmcnt(0)
	v_mfma_f32_32x32x16_bf16 v[0:15], v[146:149], v[172:175], v[0:15]
	v_sub_f32_e32 v231, v230, v194
	v_mul_f32_e32 v231, 0x3db504f3, v231
	v_mfma_f32_32x32x16_bf16 v[0:15], v[150:153], v[198:201], v[0:15]
	s_mov_b32 s6, 0x41000000
	v_cmp_ge_f32_e32 vcc, s6, v231
	v_mfma_f32_32x32x16_bf16 v[0:15], v[154:157], v[202:205], v[0:15]
	v_mfma_f32_32x32x16_bf16 v[0:15], v[158:161], v[206:209], v[0:15]
	s_nop 0
	v_mov_b32_e32 v146, v230
	v_mov_b32_e32 v147, v231
	s_branch .Lpvj_1354b

.Lpvj_1354b:
	s_cmp_eq_u64 vcc, exec
	s_cselect_b64 s[6:7], -1, 0
	s_andn2_b64 vcc, exec, s[96:97]
	s_barrier
	s_cbranch_vccnz .LBB0_1366
	s_waitcnt vmcnt(0)
	s_waitcnt vmcnt(3)
	ds_write_b128 v189, v[130:133] offset:16384
	s_waitcnt vmcnt(2)
	ds_write_b128 v190, v[134:137] offset:16384
	s_waitcnt vmcnt(1)
	ds_write_b128 v183, v[138:141] offset:49152
	s_waitcnt vmcnt(0)
	ds_write_b128 v183, v[142:145] offset:57344

.LBB0_1518:
	ds_read_b128 v[80:83], v200
	ds_read_b128 v[84:87], v200 offset:32
	ds_read_b128 v[64:67], v200 offset:128
	ds_read_b128 v[68:71], v200 offset:160
	ds_read_b128 v[88:91], v200 offset:64
	ds_read_b128 v[72:75], v200 offset:192
	ds_read_b128 v[92:95], v200 offset:96
	ds_read_b128 v[76:79], v200 offset:224
	ds_read_b128 v[208:211], v194 offset:49152
	ds_read_b128 v[220:223], v194 offset:57344
	v_add_f32_e32 v146, 0, v147
	v_add_f32_e32 v146, v148, v146
	v_add_f32_e32 v146, v149, v146
	s_waitcnt lgkmcnt(1)
	v_mfma_f32_32x32x16_bf16 v[80:95], v[208:211], v[126:129], v[80:95]
	v_add_f32_e32 v146, v160, v146
	v_add_f32_e32 v146, v161, v146
	v_add_f32_e32 v146, v207, v146
	v_add_f32_e32 v146, v159, v146
	v_add_f32_e32 v146, v206, v146
	v_add_f32_e32 v146, v151, v146
	v_add_f32_e32 v146, v153, v146
	s_waitcnt lgkmcnt(0)
	v_mfma_f32_32x32x16_bf16 v[64:79], v[220:223], v[126:129], v[64:79]
	ds_read_b128 v[208:211], v195 offset:49152
	ds_read_b128 v[220:223], v195 offset:57344
	v_add_f32_e32 v146, v154, v146
	v_add_f32_e32 v146, v155, v146
	v_exp_f32_e32 v144, v144
	v_add_f32_e32 v146, v152, v146
	v_exp_f32_e32 v145, v145
	v_add_f32_e32 v146, v156, v146
	s_waitcnt lgkmcnt(1)
	v_mfma_f32_32x32x16_bf16 v[80:95], v[208:211], v[122:125], v[80:95]
	v_exp_f32_e32 v142, v142
	v_add_f32_e32 v146, v157, v146
	v_exp_f32_e32 v143, v143
	v_add_f32_e32 v146, v158, v146
	v_exp_f32_e32 v140, v140
	v_add_f32_e32 v146, v144, v146
	v_exp_f32_e32 v141, v141
	s_waitcnt lgkmcnt(0)
	v_mfma_f32_32x32x16_bf16 v[64:79], v[220:223], v[122:125], v[64:79]
	ds_read_b128 v[208:211], v193 offset:49152
	ds_read_b128 v[220:223], v193 offset:57344
	v_add_f32_e32 v146, v145, v146
	v_exp_f32_e32 v138, v138
	v_add_f32_e32 v146, v142, v146
	v_exp_f32_e32 v139, v139
	v_add_f32_e32 v146, v143, v146
	v_exp_f32_e32 v136, v136
	s_waitcnt lgkmcnt(1)
	v_mfma_f32_32x32x16_bf16 v[80:95], v[208:211], v[118:121], v[80:95]
	v_add_f32_e32 v146, v140, v146
	v_exp_f32_e32 v137, v137
	v_add_f32_e32 v146, v141, v146
	v_exp_f32_e32 v134, v134
	v_add_f32_e32 v146, v138, v146
	v_exp_f32_e32 v135, v135
	v_add_f32_e32 v146, v139, v146
	s_waitcnt lgkmcnt(0)
	v_mfma_f32_32x32x16_bf16 v[64:79], v[220:223], v[118:121], v[64:79]
	ds_read_b128 v[208:211], v192 offset:49152
	ds_read_b128 v[220:223], v192 offset:57344
	v_exp_f32_e32 v132, v132
	v_add_f32_e32 v146, v136, v146
	v_exp_f32_e32 v133, v133
	v_add_f32_e32 v146, v137, v146
	v_exp_f32_e32 v130, v130
	v_add_f32_e32 v146, v134, v146
	s_waitcnt lgkmcnt(1)
	v_mfma_f32_32x32x16_bf16 v[80:95], v[208:211], v[114:117], v[80:95]
	v_exp_f32_e32 v131, v131
	v_add_f32_e32 v146, v135, v146
	v_add_f32_e32 v146, v132, v146
	v_add_f32_e32 v146, v133, v146
	v_add_f32_e32 v146, v130, v146
	v_add_f32_e32 v203, v131, v146
	v_mov_b32_e32 v204, v203
	s_waitcnt lgkmcnt(0)
	v_mfma_f32_32x32x16_bf16 v[64:79], v[220:223], v[114:117], v[64:79]
	ds_read_b128 v[208:211], v194 offset:49280
	ds_read_b128 v[220:223], v194 offset:57472
	v_permlane32_swap_b32_e32 v203, v204
	v_cvt_pk_bf16_f32 v146, v147, v148
	v_cvt_pk_bf16_f32 v147, v149, v160
	v_cvt_pk_bf16_f32 v148, v161, v207
	v_cvt_pk_bf16_f32 v149, v159, v206
	s_waitcnt lgkmcnt(1)
	v_mfma_f32_32x32x16_bf16 v[80:95], v[208:211], v[110:113], v[80:95]
	v_cvt_pk_bf16_f32 v206, v151, v153
	v_cvt_pk_bf16_f32 v207, v154, v155
	v_cvt_pk_bf16_f32 v153, v142, v143
	v_cvt_pk_bf16_f32 v154, v140, v141
	v_cvt_pk_bf16_f32 v155, v138, v139
	v_cvt_pk_bf16_f32 v159, v130, v131
	v_permlane32_swap_b32_e32 v146, v148
	s_waitcnt lgkmcnt(0)
	v_mfma_f32_32x32x16_bf16 v[64:79], v[220:223], v[110:113], v[64:79]
	ds_read_b128 v[208:211], v195 offset:49280
	ds_read_b128 v[220:223], v195 offset:57472
	v_permlane32_swap_b32_e32 v147, v149
	v_permlane32_swap_b32_e32 v153, v155
	s_waitcnt lgkmcnt(1)
	v_mfma_f32_32x32x16_bf16 v[80:95], v[208:211], v[106:109], v[80:95]
	s_waitcnt lgkmcnt(0)
	v_mfma_f32_32x32x16_bf16 v[64:79], v[220:223], v[106:109], v[64:79]
	ds_read_b128 v[208:211], v193 offset:49280
	ds_read_b128 v[220:223], v193 offset:57472
	s_waitcnt lgkmcnt(1)
	v_mfma_f32_32x32x16_bf16 v[80:95], v[208:211], v[102:105], v[80:95]
	s_waitcnt lgkmcnt(0)
	v_mfma_f32_32x32x16_bf16 v[64:79], v[220:223], v[102:105], v[64:79]
	ds_read_b128 v[208:211], v192 offset:49280
	ds_read_b128 v[220:223], v192 offset:57472
	s_waitcnt lgkmcnt(1)
	v_mfma_f32_32x32x16_bf16 v[80:95], v[208:211], v[98:101], v[80:95]
	v_cvt_pk_bf16_f32 v208, v152, v156
	v_cvt_pk_bf16_f32 v209, v157, v158
	v_cvt_pk_bf16_f32 v152, v144, v145
	v_cvt_pk_bf16_f32 v156, v136, v137
	v_cvt_pk_bf16_f32 v157, v134, v135
	v_cvt_pk_bf16_f32 v158, v132, v133
	v_permlane32_swap_b32_e32 v206, v208
	s_waitcnt lgkmcnt(0)
	v_mfma_f32_32x32x16_bf16 v[64:79], v[220:223], v[98:101], v[64:79]
	v_permlane32_swap_b32_e32 v207, v209
	v_permlane32_swap_b32_e32 v152, v154
	v_permlane32_swap_b32_e32 v156, v158
	v_permlane32_swap_b32_e32 v157, v159
	v_lshl_add_u64 v[130:131], v[170:171], 0, v[96:97]
	v_lshl_add_u64 v[134:135], v[166:167], 0, v[96:97]
	v_lshl_add_u64 v[138:139], v[172:173], 0, v[96:97]
	v_lshl_add_u64 v[142:143], v[168:169], 0, v[96:97]
	global_load_dwordx4 v[130:133], v[130:131], off
	s_nop 0
	global_load_dwordx4 v[134:137], v[134:135], off
	s_nop 0
	global_load_dwordx4 v[138:141], v[138:139], off
	s_nop 0
	global_load_dwordx4 v[142:145], v[142:143], off
	s_sub_i32 s6, s74, 64
	s_cmp_le_i32 s6, s3
	s_cbranch_scc0 .Lpvm_1518a
	ds_read_b64_tr_b16 v[210:211], v188 offset:0
	ds_read_b64_tr_b16 v[212:213], v188 offset:0x800
	ds_read_b64_tr_b16 v[220:221], v188 offset:0x1000
	ds_read_b64_tr_b16 v[222:223], v188 offset:0x1800
	ds_read_b64_tr_b16 v[224:225], v188 offset:0x2000
	ds_read_b64_tr_b16 v[226:227], v188 offset:0x2800
	ds_read_b64_tr_b16 v[238:239], v188 offset:0x3000
	ds_read_b64_tr_b16 v[240:241], v188 offset:0x3800
	s_waitcnt lgkmcnt(0)
	s_nop 0
	v_mfma_f32_32x32x16_bf16 v[0:15], v[146:149], v[210:213], v[0:15]
	v_max_f32_e32 v230, v81, v81
	v_max_f32_e32 v231, v80, v80
	v_max_f32_e32 v230, v231, v230
	ds_read_b64_tr_b16 v[210:211], v188 offset:0x200
	ds_read_b64_tr_b16 v[212:213], v188 offset:0xa00
	v_mfma_f32_32x32x16_bf16 v[0:15], v[206:209], v[220:223], v[0:15]
	v_max3_f32 v230, v230, v82, v83
	v_max3_f32 v230, v230, v84, v85
	v_max3_f32 v230, v230, v86, v87
	ds_read_b64_tr_b16 v[220:221], v188 offset:0x1200
	ds_read_b64_tr_b16 v[222:223], v188 offset:0x1a00
	v_mfma_f32_32x32x16_bf16 v[0:15], v[152:155], v[224:227], v[0:15]
	v_max3_f32 v230, v230, v88, v89
	v_max3_f32 v230, v230, v90, v91
	v_max3_f32 v230, v230, v92, v93
	ds_read_b64_tr_b16 v[224:225], v188 offset:0x2200
	ds_read_b64_tr_b16 v[226:227], v188 offset:0x2a00
	v_mfma_f32_32x32x16_bf16 v[0:15], v[156:159], v[238:241], v[0:15]
	v_max3_f32 v230, v230, v94, v95
	v_max3_f32 v230, v230, v64, v65
	v_max3_f32 v230, v230, v66, v67
	ds_read_b64_tr_b16 v[238:239], v188 offset:0x3200
	ds_read_b64_tr_b16 v[240:241], v188 offset:0x3a00
	s_waitcnt lgkmcnt(0)
	v_mfma_f32_32x32x16_bf16 v[48:63], v[146:149], v[210:213], v[48:63]
	v_max3_f32 v230, v230, v68, v69
	v_max3_f32 v230, v230, v70, v71
	v_max3_f32 v230, v230, v72, v73
	ds_read_b64_tr_b16 v[210:211], v188 offset:0x400
	ds_read_b64_tr_b16 v[212:213], v188 offset:0xc00
	v_mfma_f32_32x32x16_bf16 v[48:63], v[206:209], v[220:223], v[48:63]
	v_max3_f32 v230, v230, v74, v75
	v_max3_f32 v230, v230, v76, v77
	v_max3_f32 v230, v230, v78, v79
	ds_read_b64_tr_b16 v[220:221], v188 offset:0x1400
	ds_read_b64_tr_b16 v[222:223], v188 offset:0x1c00
	v_mfma_f32_32x32x16_bf16 v[48:63], v[152:155], v[224:227], v[48:63]
	v_mov_b32_e32 v231, v230
	s_nop 1
	v_permlane32_swap_b32_e32 v230, v231
	ds_read_b64_tr_b16 v[224:225], v188 offset:0x2400
	ds_read_b64_tr_b16 v[226:227], v188 offset:0x2c00
	v_mfma_f32_32x32x16_bf16 v[48:63], v[156:159], v[238:241], v[48:63]
	v_max_f32_e32 v231, v231, v231
	v_max_f32_e32 v230, v230, v230
	v_max_f32_e32 v230, v230, v231
	ds_read_b64_tr_b16 v[238:239], v188 offset:0x3400
	ds_read_b64_tr_b16 v[240:241], v188 offset:0x3c00
	s_waitcnt lgkmcnt(0)
	v_mfma_f32_32x32x16_bf16 v[32:47], v[146:149], v[210:213], v[32:47]
	v_sub_f32_e32 v231, v230, v150
	v_mul_f32_e32 v231, 0x3db504f3, v231
	s_mov_b32 s6, 0x41000000
	ds_read_b64_tr_b16 v[210:211], v188 offset:0x600
	ds_read_b64_tr_b16 v[212:213], v188 offset:0xe00
	v_mfma_f32_32x32x16_bf16 v[32:47], v[206:209], v[220:223], v[32:47]
	v_cmp_ge_f32_e32 vcc, s6, v231
	v_max_f32_e32 v231, v150, v150
	v_max_f32_e32 v230, v231, v230
	ds_read_b64_tr_b16 v[220:221], v188 offset:0x1600
	ds_read_b64_tr_b16 v[222:223], v188 offset:0x1e00
	v_mfma_f32_32x32x16_bf16 v[32:47], v[152:155], v[224:227], v[32:47]
	v_sub_f32_e32 v231, v150, v230
	v_mul_f32_e32 v231, 0x3e0293ee, v231
	v_exp_f32_e32 v231, v231
	ds_read_b64_tr_b16 v[224:225], v188 offset:0x2600
	ds_read_b64_tr_b16 v[226:227], v188 offset:0x2e00
	v_mfma_f32_32x32x16_bf16 v[32:47], v[156:159], v[238:241], v[32:47]
	ds_read_b64_tr_b16 v[238:239], v188 offset:0x3600
	ds_read_b64_tr_b16 v[240:241], v188 offset:0x3e00
	s_waitcnt lgkmcnt(0)
	v_mfma_f32_32x32x16_bf16 v[16:31], v[146:149], v[210:213], v[16:31]
	v_mfma_f32_32x32x16_bf16 v[16:31], v[206:209], v[220:223], v[16:31]
	v_mfma_f32_32x32x16_bf16 v[16:31], v[152:155], v[224:227], v[16:31]
	v_mfma_f32_32x32x16_bf16 v[16:31], v[156:159], v[238:241], v[16:31]
	s_nop 0
	v_mov_b32_e32 v146, v230
	v_mov_b32_e32 v147, v231
	s_branch .Lpvj_1518a
.Lpvm_1518a:
	ds_read_b64_tr_b16 v[210:211], v188 offset:0
	ds_read_b64_tr_b16 v[212:213], v188 offset:0x800
	ds_read_b64_tr_b16 v[220:221], v188 offset:0x1000
	ds_read_b64_tr_b16 v[222:223], v188 offset:0x1800
	ds_read_b64_tr_b16 v[224:225], v188 offset:0x2000
	ds_read_b64_tr_b16 v[226:227], v188 offset:0x2800
	ds_read_b64_tr_b16 v[238:239], v188 offset:0x3000
	ds_read_b64_tr_b16 v[240:241], v188 offset:0x3800
	s_waitcnt lgkmcnt(0)
	s_nop 0
	v_mfma_f32_32x32x16_bf16 v[0:15], v[146:149], v[210:213], v[0:15]
	ds_read_b64_tr_b16 v[210:211], v188 offset:0x200
	ds_read_b64_tr_b16 v[212:213], v188 offset:0xa00
	v_mfma_f32_32x32x16_bf16 v[0:15], v[206:209], v[220:223], v[0:15]
	ds_read_b64_tr_b16 v[220:221], v188 offset:0x1200
	ds_read_b64_tr_b16 v[222:223], v188 offset:0x1a00
	v_mfma_f32_32x32x16_bf16 v[0:15], v[152:155], v[224:227], v[0:15]
	ds_read_b64_tr_b16 v[224:225], v188 offset:0x2200
	ds_read_b64_tr_b16 v[226:227], v188 offset:0x2a00
	v_mfma_f32_32x32x16_bf16 v[0:15], v[156:159], v[238:241], v[0:15]
	ds_read_b64_tr_b16 v[238:239], v188 offset:0x3200
	ds_read_b64_tr_b16 v[240:241], v188 offset:0x3a00
	s_waitcnt lgkmcnt(0)
	v_mfma_f32_32x32x16_bf16 v[48:63], v[146:149], v[210:213], v[48:63]
	ds_read_b64_tr_b16 v[210:211], v188 offset:0x400
	ds_read_b64_tr_b16 v[212:213], v188 offset:0xc00
	v_mfma_f32_32x32x16_bf16 v[48:63], v[206:209], v[220:223], v[48:63]
	ds_read_b64_tr_b16 v[220:221], v188 offset:0x1400
	ds_read_b64_tr_b16 v[222:223], v188 offset:0x1c00
	v_mfma_f32_32x32x16_bf16 v[48:63], v[152:155], v[224:227], v[48:63]
	ds_read_b64_tr_b16 v[224:225], v188 offset:0x2400
	ds_read_b64_tr_b16 v[226:227], v188 offset:0x2c00
	v_mfma_f32_32x32x16_bf16 v[48:63], v[156:159], v[238:241], v[48:63]
	ds_read_b64_tr_b16 v[238:239], v188 offset:0x3400
	ds_read_b64_tr_b16 v[240:241], v188 offset:0x3c00
	s_waitcnt lgkmcnt(0)
	v_mfma_f32_32x32x16_bf16 v[32:47], v[146:149], v[210:213], v[32:47]
	ds_read_b64_tr_b16 v[210:211], v188 offset:0x600
	ds_read_b64_tr_b16 v[212:213], v188 offset:0xe00
	v_mfma_f32_32x32x16_bf16 v[32:47], v[206:209], v[220:223], v[32:47]
	ds_read_b64_tr_b16 v[220:221], v188 offset:0x1600
	ds_read_b64_tr_b16 v[222:223], v188 offset:0x1e00
	v_mfma_f32_32x32x16_bf16 v[32:47], v[152:155], v[224:227], v[32:47]
	ds_read_b64_tr_b16 v[224:225], v188 offset:0x2600
	ds_read_b64_tr_b16 v[226:227], v188 offset:0x2e00
	v_mfma_f32_32x32x16_bf16 v[32:47], v[156:159], v[238:241], v[32:47]
	ds_read_b64_tr_b16 v[238:239], v188 offset:0x3600
	ds_read_b64_tr_b16 v[240:241], v188 offset:0x3e00
	s_waitcnt lgkmcnt(0)
	v_mfma_f32_32x32x16_bf16 v[16:31], v[146:149], v[210:213], v[16:31]
	s_sub_i32 s6, s74, 64
	s_cmp_le_i32 s6, s3
	v_mfma_f32_32x32x16_bf16 v[16:31], v[206:209], v[220:223], v[16:31]
	v_mfma_f32_32x32x16_bf16 v[16:31], v[152:155], v[224:227], v[16:31]
	v_mfma_f32_32x32x16_bf16 v[16:31], v[156:159], v[238:241], v[16:31]
	s_cbranch_scc1 .LBB0_1520
	v_add_u32_e32 v146, 64, v202
	v_cmp_gt_i32_e64 s[66:67], 26, v146
	v_cmp_gt_i32_e64 s[68:69], 27, v146
	v_cmp_gt_i32_e64 s[64:65], 25, v146
	s_and_b64 s[66:67], s[68:69], s[66:67]
	v_cmp_gt_i32_e64 s[62:63], 24, v146
	s_and_b64 s[64:65], s[66:67], s[64:65]
	v_cmp_gt_i32_e64 s[60:61], 19, v146
	s_and_b64 s[62:63], s[64:65], s[62:63]
	v_cmp_gt_i32_e64 s[58:59], 18, v146
	s_and_b64 s[60:61], s[62:63], s[60:61]
	v_cmp_gt_i32_e64 s[56:57], 17, v146
	s_and_b64 s[58:59], s[60:61], s[58:59]
	v_cmp_gt_i32_e64 s[54:55], 16, v146
	s_and_b64 s[56:57], s[58:59], s[56:57]
	v_cmp_gt_i32_e64 s[52:53], 11, v146
	s_and_b64 s[54:55], s[56:57], s[54:55]
	v_cmp_gt_i32_e64 s[50:51], 10, v146
	s_and_b64 s[52:53], s[54:55], s[52:53]
	v_cmp_gt_i32_e64 s[48:49], 9, v146
	s_and_b64 s[50:51], s[52:53], s[50:51]
	v_cmp_gt_i32_e64 s[46:47], 8, v146
	s_and_b64 s[48:49], s[50:51], s[48:49]
	v_cmp_gt_i32_e64 s[44:45], 3, v146
	s_and_b64 s[46:47], s[48:49], s[46:47]
	v_cmp_gt_i32_e64 s[42:43], 2, v146
	s_and_b64 s[44:45], s[46:47], s[44:45]
	v_cmp_gt_i32_e64 s[38:39], 1, v146
	s_and_b64 s[42:43], s[44:45], s[42:43]
	v_cmp_gt_i32_e64 s[36:37], 0, v146
	s_and_b64 s[38:39], s[42:43], s[38:39]
	s_and_b64 s[36:37], s[38:39], s[36:37]
	v_cmp_gt_i32_e64 s[34:35], 58, v146
	v_cndmask_b32_e64 v80, v80, v232, s[36:37]
	v_cmp_gt_i32_e64 s[36:37], 59, v146
	v_cmp_gt_i32_e64 s[30:31], 57, v146
	s_and_b64 s[34:35], s[36:37], s[34:35]
	v_cmp_gt_i32_e64 s[28:29], 56, v146
	s_and_b64 s[30:31], s[34:35], s[30:31]
	v_cmp_gt_i32_e64 s[26:27], 51, v146
	s_and_b64 s[28:29], s[30:31], s[28:29]
	v_cmp_gt_i32_e64 s[24:25], 50, v146
	s_and_b64 s[26:27], s[28:29], s[26:27]
	v_cmp_gt_i32_e64 s[22:23], 49, v146
	s_and_b64 s[24:25], s[26:27], s[24:25]
	v_cmp_gt_i32_e64 s[20:21], 48, v146
	s_and_b64 s[22:23], s[24:25], s[22:23]
	v_cmp_gt_i32_e64 s[18:19], 43, v146
	s_and_b64 s[20:21], s[22:23], s[20:21]
	v_cmp_gt_i32_e64 s[16:17], 42, v146
	s_and_b64 s[18:19], s[20:21], s[18:19]
	v_cmp_gt_i32_e64 s[14:15], 41, v146
	s_and_b64 s[16:17], s[18:19], s[16:17]
	v_cmp_gt_i32_e64 s[12:13], 40, v146
	s_and_b64 s[14:15], s[16:17], s[14:15]
	v_cmp_gt_i32_e64 s[10:11], 35, v146
	s_and_b64 s[12:13], s[14:15], s[12:13]
	v_cmp_gt_i32_e64 s[8:9], 34, v146
	s_and_b64 s[10:11], s[12:13], s[10:11]
	v_cmp_gt_i32_e64 s[6:7], 33, v146
	s_and_b64 s[8:9], s[10:11], s[8:9]
	v_cmp_gt_i32_e32 vcc, 32, v146
	s_and_b64 s[6:7], s[8:9], s[6:7]
	s_and_b64 vcc, s[6:7], vcc
	v_cndmask_b32_e64 v95, v95, v232, s[68:69]
	v_cndmask_b32_e64 v94, v94, v232, s[66:67]
	v_cndmask_b32_e64 v93, v93, v232, s[64:65]
	v_cndmask_b32_e64 v92, v92, v232, s[62:63]
	v_cndmask_b32_e64 v91, v91, v232, s[60:61]
	v_cndmask_b32_e64 v90, v90, v232, s[58:59]
	v_cndmask_b32_e64 v89, v89, v232, s[56:57]
	v_cndmask_b32_e64 v88, v88, v232, s[54:55]
	v_cndmask_b32_e64 v87, v87, v232, s[52:53]
	v_cndmask_b32_e64 v86, v86, v232, s[50:51]
	v_cndmask_b32_e64 v85, v85, v232, s[48:49]
	v_cndmask_b32_e64 v84, v84, v232, s[46:47]
	v_cndmask_b32_e64 v83, v83, v232, s[44:45]
	v_cndmask_b32_e64 v82, v82, v232, s[42:43]
	v_cndmask_b32_e64 v81, v81, v232, s[38:39]
	v_cndmask_b32_e64 v79, v79, v232, s[36:37]
	v_cndmask_b32_e64 v78, v78, v232, s[34:35]
	v_cndmask_b32_e64 v77, v77, v232, s[30:31]
	v_cndmask_b32_e64 v76, v76, v232, s[28:29]
	v_cndmask_b32_e64 v75, v75, v232, s[26:27]
	v_cndmask_b32_e64 v74, v74, v232, s[24:25]
	v_cndmask_b32_e64 v73, v73, v232, s[22:23]
	v_cndmask_b32_e64 v72, v72, v232, s[20:21]
	v_cndmask_b32_e64 v71, v71, v232, s[18:19]
	v_cndmask_b32_e64 v70, v70, v232, s[16:17]
	v_cndmask_b32_e64 v69, v69, v232, s[14:15]
	v_cndmask_b32_e64 v68, v68, v232, s[12:13]
	v_cndmask_b32_e64 v67, v67, v232, s[10:11]
	v_cndmask_b32_e64 v66, v66, v232, s[8:9]
	v_cndmask_b32_e64 v65, v65, v232, s[6:7]
	v_cndmask_b32_e32 v64, v64, v232, vcc

.Lpvj_1518a:
	s_cmp_eq_u64 vcc, exec
	s_cselect_b64 s[6:7], -1, 0
	s_barrier
	s_waitcnt vmcnt(0)
	v_cndmask_b32_e64 v205, v147, 1.0, s[6:7]
	v_cmp_gt_f32_e32 vcc, 1.0, v205
	s_waitcnt vmcnt(3)
	ds_write_b128 v197, v[130:133]
	s_waitcnt vmcnt(2)
	ds_write_b128 v198, v[134:137]
	s_waitcnt vmcnt(1)
	ds_write_b128 v186, v[138:141] offset:32768
	s_waitcnt vmcnt(0)
	ds_write_b128 v186, v[142:145] offset:40960
	s_cbranch_vccz .LBB0_1524
	s_and_saveexec_b64 s[8:9], s[4:5]
	ds_write_b32 v201, v205 offset:128
	s_or_b64 exec, exec, s[8:9]
	s_waitcnt lgkmcnt(0)
	ds_read_b128 v[152:155], v191 offset:224
	ds_read_b128 v[156:159], v191 offset:192
	ds_read_b128 v[206:209], v191 offset:160
	ds_read_b128 v[210:213], v191 offset:128
	s_waitcnt lgkmcnt(3)
	v_pk_mul_f32 v[14:15], v[14:15], v[154:155]
	s_waitcnt lgkmcnt(2)
	v_pk_mul_f32 v[10:11], v[10:11], v[158:159]
	s_waitcnt lgkmcnt(1)
	v_pk_mul_f32 v[6:7], v[6:7], v[208:209]
	s_waitcnt lgkmcnt(0)
	v_pk_mul_f32 v[2:3], v[2:3], v[212:213]
	v_pk_mul_f32 v[12:13], v[12:13], v[152:153]
	v_pk_mul_f32 v[8:9], v[8:9], v[156:157]
	v_pk_mul_f32 v[4:5], v[4:5], v[206:207]
	v_pk_mul_f32 v[0:1], v[0:1], v[210:211]
	v_pk_mul_f32 v[62:63], v[62:63], v[154:155]
	v_pk_mul_f32 v[58:59], v[58:59], v[158:159]
	v_pk_mul_f32 v[54:55], v[54:55], v[208:209]
	v_pk_mul_f32 v[50:51], v[50:51], v[212:213]
	v_pk_mul_f32 v[60:61], v[60:61], v[152:153]
	v_pk_mul_f32 v[56:57], v[56:57], v[156:157]
	v_pk_mul_f32 v[52:53], v[52:53], v[206:207]
	v_pk_mul_f32 v[48:49], v[48:49], v[210:211]
	v_pk_mul_f32 v[46:47], v[46:47], v[154:155]
	v_pk_mul_f32 v[42:43], v[42:43], v[158:159]
	v_pk_mul_f32 v[38:39], v[38:39], v[208:209]
	v_pk_mul_f32 v[34:35], v[34:35], v[212:213]
	v_pk_mul_f32 v[44:45], v[44:45], v[152:153]
	v_pk_mul_f32 v[40:41], v[40:41], v[156:157]
	v_pk_mul_f32 v[36:37], v[36:37], v[206:207]
	v_pk_mul_f32 v[32:33], v[32:33], v[210:211]
	v_pk_mul_f32 v[30:31], v[30:31], v[154:155]
	v_pk_mul_f32 v[26:27], v[26:27], v[158:159]
	v_pk_mul_f32 v[22:23], v[22:23], v[208:209]
	v_pk_mul_f32 v[18:19], v[18:19], v[212:213]
	v_pk_mul_f32 v[28:29], v[28:29], v[152:153]
	v_pk_mul_f32 v[24:25], v[24:25], v[156:157]
	v_pk_mul_f32 v[20:21], v[20:21], v[206:207]
	v_pk_mul_f32 v[16:17], v[16:17], v[210:211]

.LBB0_1526:
	s_cmp_le_i32 s74, s3
	s_cbranch_scc0 .Lpvm_1518b
	ds_read_b64_tr_b16 v[210:211], v188 offset:0x4000
	ds_read_b64_tr_b16 v[212:213], v188 offset:0x4800
	ds_read_b64_tr_b16 v[220:221], v188 offset:0x5000
	ds_read_b64_tr_b16 v[222:223], v188 offset:0x5800
	ds_read_b64_tr_b16 v[224:225], v188 offset:0x6000
	ds_read_b64_tr_b16 v[226:227], v188 offset:0x6800
	ds_read_b64_tr_b16 v[238:239], v188 offset:0x7000
	ds_read_b64_tr_b16 v[240:241], v188 offset:0x7800
	s_waitcnt lgkmcnt(0)
	s_nop 0
	v_mfma_f32_32x32x16_bf16 v[0:15], v[146:149], v[210:213], v[0:15]
	v_max_f32_e32 v230, v81, v81
	v_max_f32_e32 v231, v80, v80
	ds_read_b64_tr_b16 v[210:211], v188 offset:0x4200
	ds_read_b64_tr_b16 v[212:213], v188 offset:0x4a00
	v_mfma_f32_32x32x16_bf16 v[0:15], v[150:153], v[220:223], v[0:15]
	v_max_f32_e32 v230, v231, v230
	v_max3_f32 v230, v230, v82, v83
	ds_read_b64_tr_b16 v[220:221], v188 offset:0x5200
	ds_read_b64_tr_b16 v[222:223], v188 offset:0x5a00
	v_mfma_f32_32x32x16_bf16 v[0:15], v[154:157], v[224:227], v[0:15]
	v_max3_f32 v230, v230, v84, v85
	v_max3_f32 v230, v230, v86, v87
	ds_read_b64_tr_b16 v[224:225], v188 offset:0x6200
	ds_read_b64_tr_b16 v[226:227], v188 offset:0x6a00
	v_mfma_f32_32x32x16_bf16 v[0:15], v[158:161], v[238:241], v[0:15]
	v_max3_f32 v230, v230, v88, v89
	v_max3_f32 v230, v230, v90, v91
	ds_read_b64_tr_b16 v[238:239], v188 offset:0x7200
	ds_read_b64_tr_b16 v[240:241], v188 offset:0x7a00
	s_waitcnt lgkmcnt(0)
	v_mfma_f32_32x32x16_bf16 v[48:63], v[146:149], v[210:213], v[48:63]
	v_max3_f32 v230, v230, v92, v93
	v_max3_f32 v230, v230, v94, v95
	ds_read_b64_tr_b16 v[210:211], v188 offset:0x4400
	ds_read_b64_tr_b16 v[212:213], v188 offset:0x4c00
	v_mfma_f32_32x32x16_bf16 v[48:63], v[150:153], v[220:223], v[48:63]
	v_max3_f32 v230, v230, v64, v65
	v_max3_f32 v230, v230, v66, v67
	ds_read_b64_tr_b16 v[220:221], v188 offset:0x5400
	ds_read_b64_tr_b16 v[222:223], v188 offset:0x5c00
	v_mfma_f32_32x32x16_bf16 v[48:63], v[154:157], v[224:227], v[48:63]
	v_max3_f32 v230, v230, v68, v69
	v_max3_f32 v230, v230, v70, v71
	ds_read_b64_tr_b16 v[224:225], v188 offset:0x6400
	ds_read_b64_tr_b16 v[226:227], v188 offset:0x6c00
	v_mfma_f32_32x32x16_bf16 v[48:63], v[158:161], v[238:241], v[48:63]
	v_max3_f32 v230, v230, v72, v73
	v_max3_f32 v230, v230, v74, v75
	ds_read_b64_tr_b16 v[238:239], v188 offset:0x7400
	ds_read_b64_tr_b16 v[240:241], v188 offset:0x7c00
	s_waitcnt lgkmcnt(0)
	v_mfma_f32_32x32x16_bf16 v[32:47], v[146:149], v[210:213], v[32:47]
	v_max3_f32 v230, v230, v76, v77
	v_max3_f32 v230, v230, v78, v79
	ds_read_b64_tr_b16 v[210:211], v188 offset:0x4600
	ds_read_b64_tr_b16 v[212:213], v188 offset:0x4e00
	v_mfma_f32_32x32x16_bf16 v[32:47], v[150:153], v[220:223], v[32:47]
	v_mov_b32_e32 v231, v230
	s_nop 1
	ds_read_b64_tr_b16 v[220:221], v188 offset:0x5600
	ds_read_b64_tr_b16 v[222:223], v188 offset:0x5e00
	v_mfma_f32_32x32x16_bf16 v[32:47], v[154:157], v[224:227], v[32:47]
	v_permlane32_swap_b32_e32 v230, v231
	v_max_f32_e32 v231, v231, v231
	ds_read_b64_tr_b16 v[224:225], v188 offset:0x6600
	ds_read_b64_tr_b16 v[226:227], v188 offset:0x6e00
	v_mfma_f32_32x32x16_bf16 v[32:47], v[158:161], v[238:241], v[32:47]
	v_max_f32_e32 v230, v230, v230
	v_max_f32_e32 v230, v230, v231
	ds_read_b64_tr_b16 v[238:239], v188 offset:0x7600
	ds_read_b64_tr_b16 v[240:241], v188 offset:0x7e00
	s_waitcnt lgkmcnt(0)
	v_mfma_f32_32x32x16_bf16 v[16:31], v[146:149], v[210:213], v[16:31]
	v_sub_f32_e32 v231, v230, v206
	v_mul_f32_e32 v231, 0x3db504f3, v231
	v_mfma_f32_32x32x16_bf16 v[16:31], v[150:153], v[220:223], v[16:31]
	s_mov_b32 s6, 0x41000000
	v_cmp_ge_f32_e32 vcc, s6, v231
	v_mfma_f32_32x32x16_bf16 v[16:31], v[154:157], v[224:227], v[16:31]
	v_mfma_f32_32x32x16_bf16 v[16:31], v[158:161], v[238:241], v[16:31]
	s_nop 0
	v_mov_b32_e32 v146, v230
	v_mov_b32_e32 v147, v231
	s_branch .Lpvj_1518b

.Lpvj_1518b:
	s_cmp_eq_u64 vcc, exec
	s_cselect_b64 s[6:7], -1, 0
	s_andn2_b64 vcc, exec, s[72:73]
	s_barrier
	s_cbranch_vccnz .LBB0_1530
	s_waitcnt vmcnt(0)
	s_waitcnt vmcnt(3)
	ds_write_b128 v197, v[130:133] offset:16384
	s_waitcnt vmcnt(2)
	ds_write_b128 v198, v[134:137] offset:16384
	s_waitcnt vmcnt(1)
	ds_write_b128 v186, v[138:141] offset:49152
	s_waitcnt vmcnt(0)
	ds_write_b128 v186, v[142:145] offset:57344
